# v072 + GEMM epilogue global stores made write-through (sc0 sc1) so the grid-barrier L2 write-back has little left to flush
# baseline (speedup 1.0000x reference)
.Lgemm_epi0:
	s_mov_b32 s56, 0xbfb8aa3b
	v_lshl_or_b32 v156, s47, 7, v148
	v_ashrrev_i32_e32 v157, 31, v156
	v_lshl_add_u32 v152, s22, 8, v146
	v_lshlrev_b64 v[234:235], 1, v[156:157]
	v_lshl_add_u64 v[234:235], s[4:5], 0, v[234:235]
	s_and_b64 vcc, exec, s[2:3]
	s_mov_b32 s47, s8
	s_mov_b32 s22, s12
	s_mov_b64 s[26:27], s[20:21]
	s_mov_b64 s[24:25], s[14:15]
	v_mad_i64_i32 v[236:237], s[0:1], v152, s46, v[234:235]
	v_pk_mul_f32 v[226:227], v[126:127], s[56:57] op_sel_hi:[1,0]
	v_pk_mul_f32 v[228:229], v[128:129], s[56:57] op_sel_hi:[1,0]
	v_pk_mul_f32 v[230:231], v[122:123], s[56:57] op_sel_hi:[1,0]
	v_pk_mul_f32 v[232:233], v[124:125], s[56:57] op_sel_hi:[1,0]
	v_exp_f32_e32 v226, v226
	v_exp_f32_e32 v227, v227
	v_exp_f32_e32 v228, v228
	v_exp_f32_e32 v229, v229
	v_exp_f32_e32 v230, v230
	v_exp_f32_e32 v231, v231
	v_exp_f32_e32 v232, v232
	v_exp_f32_e32 v233, v233
	v_pk_add_f32 v[226:227], v[226:227], 1.0 op_sel_hi:[1,0]
	v_pk_add_f32 v[228:229], v[228:229], 1.0 op_sel_hi:[1,0]
	v_pk_add_f32 v[230:231], v[230:231], 1.0 op_sel_hi:[1,0]
	v_pk_add_f32 v[232:233], v[232:233], 1.0 op_sel_hi:[1,0]
	v_rcp_f32_e32 v226, v226
	v_rcp_f32_e32 v227, v227
	v_rcp_f32_e32 v228, v228
	v_rcp_f32_e32 v229, v229
	v_rcp_f32_e32 v230, v230
	v_rcp_f32_e32 v231, v231
	v_rcp_f32_e32 v232, v232
	v_rcp_f32_e32 v233, v233
	v_pk_mul_f32 v[126:127], v[126:127], v[226:227]
	v_pk_mul_f32 v[128:129], v[128:129], v[228:229]
	v_pk_mul_f32 v[122:123], v[122:123], v[230:231]
	v_pk_mul_f32 v[124:125], v[124:125], v[232:233]
	v_pk_mul_f32 v[118:119], v[126:127], v[118:119]
	v_pk_mul_f32 v[120:121], v[128:129], v[120:121]
	v_pk_mul_f32 v[114:115], v[122:123], v[114:115]
	v_pk_mul_f32 v[116:117], v[124:125], v[116:117]
	v_cvt_pk_bf16_f32 v118, v118, v119
	v_cvt_pk_bf16_f32 v119, v120, v121
	v_cvt_pk_bf16_f32 v120, v114, v115
	v_cvt_pk_bf16_f32 v121, v116, v117
	global_store_dwordx4 v[236:237], v[118:121], off sc0 sc1
	v_add_u32_e32 v153, 16, v152
	v_mad_i64_i32 v[238:239], s[0:1], v153, s46, v[234:235]
	v_pk_mul_f32 v[226:227], v[110:111], s[56:57] op_sel_hi:[1,0]
	v_pk_mul_f32 v[228:229], v[112:113], s[56:57] op_sel_hi:[1,0]
	v_pk_mul_f32 v[230:231], v[106:107], s[56:57] op_sel_hi:[1,0]
	v_pk_mul_f32 v[232:233], v[108:109], s[56:57] op_sel_hi:[1,0]
	v_exp_f32_e32 v226, v226
	v_exp_f32_e32 v227, v227
	v_exp_f32_e32 v228, v228
	v_exp_f32_e32 v229, v229
	v_exp_f32_e32 v230, v230
	v_exp_f32_e32 v231, v231
	v_exp_f32_e32 v232, v232
	v_exp_f32_e32 v233, v233
	v_pk_add_f32 v[226:227], v[226:227], 1.0 op_sel_hi:[1,0]
	v_pk_add_f32 v[228:229], v[228:229], 1.0 op_sel_hi:[1,0]
	v_pk_add_f32 v[230:231], v[230:231], 1.0 op_sel_hi:[1,0]
	v_pk_add_f32 v[232:233], v[232:233], 1.0 op_sel_hi:[1,0]
	v_rcp_f32_e32 v226, v226
	v_rcp_f32_e32 v227, v227
	v_rcp_f32_e32 v228, v228
	v_rcp_f32_e32 v229, v229
	v_rcp_f32_e32 v230, v230
	v_rcp_f32_e32 v231, v231
	v_rcp_f32_e32 v232, v232
	v_rcp_f32_e32 v233, v233
	v_pk_mul_f32 v[110:111], v[110:111], v[226:227]
	v_pk_mul_f32 v[112:113], v[112:113], v[228:229]
	v_pk_mul_f32 v[106:107], v[106:107], v[230:231]
	v_pk_mul_f32 v[108:109], v[108:109], v[232:233]
	v_pk_mul_f32 v[102:103], v[110:111], v[102:103]
	v_pk_mul_f32 v[104:105], v[112:113], v[104:105]
	v_pk_mul_f32 v[98:99], v[106:107], v[98:99]
	v_pk_mul_f32 v[100:101], v[108:109], v[100:101]
	v_cvt_pk_bf16_f32 v102, v102, v103
	v_cvt_pk_bf16_f32 v103, v104, v105
	v_cvt_pk_bf16_f32 v104, v98, v99
	v_cvt_pk_bf16_f32 v105, v100, v101
	global_store_dwordx4 v[238:239], v[102:105], off sc0 sc1
	v_add_u32_e32 v153, 32, v152
	v_mad_i64_i32 v[236:237], s[0:1], v153, s46, v[234:235]
	v_pk_mul_f32 v[226:227], v[94:95], s[56:57] op_sel_hi:[1,0]
	v_pk_mul_f32 v[228:229], v[96:97], s[56:57] op_sel_hi:[1,0]
	v_pk_mul_f32 v[230:231], v[90:91], s[56:57] op_sel_hi:[1,0]
	v_pk_mul_f32 v[232:233], v[92:93], s[56:57] op_sel_hi:[1,0]
	v_exp_f32_e32 v226, v226
	v_exp_f32_e32 v227, v227
	v_exp_f32_e32 v228, v228
	v_exp_f32_e32 v229, v229
	v_exp_f32_e32 v230, v230
	v_exp_f32_e32 v231, v231
	v_exp_f32_e32 v232, v232
	v_exp_f32_e32 v233, v233
	v_pk_add_f32 v[226:227], v[226:227], 1.0 op_sel_hi:[1,0]
	v_pk_add_f32 v[228:229], v[228:229], 1.0 op_sel_hi:[1,0]
	v_pk_add_f32 v[230:231], v[230:231], 1.0 op_sel_hi:[1,0]
	v_pk_add_f32 v[232:233], v[232:233], 1.0 op_sel_hi:[1,0]
	v_rcp_f32_e32 v226, v226
	v_rcp_f32_e32 v227, v227
	v_rcp_f32_e32 v228, v228
	v_rcp_f32_e32 v229, v229
	v_rcp_f32_e32 v230, v230
	v_rcp_f32_e32 v231, v231
	v_rcp_f32_e32 v232, v232
	v_rcp_f32_e32 v233, v233
	v_pk_mul_f32 v[94:95], v[94:95], v[226:227]
	v_pk_mul_f32 v[96:97], v[96:97], v[228:229]
	v_pk_mul_f32 v[90:91], v[90:91], v[230:231]
	v_pk_mul_f32 v[92:93], v[92:93], v[232:233]
	v_pk_mul_f32 v[86:87], v[94:95], v[86:87]
	v_pk_mul_f32 v[88:89], v[96:97], v[88:89]
	v_pk_mul_f32 v[82:83], v[90:91], v[82:83]
	v_pk_mul_f32 v[84:85], v[92:93], v[84:85]
	v_cvt_pk_bf16_f32 v86, v86, v87
	v_cvt_pk_bf16_f32 v87, v88, v89
	v_cvt_pk_bf16_f32 v88, v82, v83
	v_cvt_pk_bf16_f32 v89, v84, v85
	global_store_dwordx4 v[236:237], v[86:89], off sc0 sc1
	v_add_u32_e32 v153, 48, v152
	v_mad_i64_i32 v[238:239], s[0:1], v153, s46, v[234:235]
	v_pk_mul_f32 v[226:227], v[78:79], s[56:57] op_sel_hi:[1,0]
	v_pk_mul_f32 v[228:229], v[80:81], s[56:57] op_sel_hi:[1,0]
	v_pk_mul_f32 v[230:231], v[74:75], s[56:57] op_sel_hi:[1,0]
	v_pk_mul_f32 v[232:233], v[76:77], s[56:57] op_sel_hi:[1,0]
	v_exp_f32_e32 v226, v226
	v_exp_f32_e32 v227, v227
	v_exp_f32_e32 v228, v228
	v_exp_f32_e32 v229, v229
	v_exp_f32_e32 v230, v230
	v_exp_f32_e32 v231, v231
	v_exp_f32_e32 v232, v232
	v_exp_f32_e32 v233, v233
	v_pk_add_f32 v[226:227], v[226:227], 1.0 op_sel_hi:[1,0]
	v_pk_add_f32 v[228:229], v[228:229], 1.0 op_sel_hi:[1,0]
	v_pk_add_f32 v[230:231], v[230:231], 1.0 op_sel_hi:[1,0]
	v_pk_add_f32 v[232:233], v[232:233], 1.0 op_sel_hi:[1,0]
	v_rcp_f32_e32 v226, v226
	v_rcp_f32_e32 v227, v227
	v_rcp_f32_e32 v228, v228
	v_rcp_f32_e32 v229, v229
	v_rcp_f32_e32 v230, v230
	v_rcp_f32_e32 v231, v231
	v_rcp_f32_e32 v232, v232
	v_rcp_f32_e32 v233, v233
	v_pk_mul_f32 v[78:79], v[78:79], v[226:227]
	v_pk_mul_f32 v[80:81], v[80:81], v[228:229]
	v_pk_mul_f32 v[74:75], v[74:75], v[230:231]
	v_pk_mul_f32 v[76:77], v[76:77], v[232:233]
	v_pk_mul_f32 v[70:71], v[78:79], v[70:71]
	v_pk_mul_f32 v[72:73], v[80:81], v[72:73]
	v_pk_mul_f32 v[66:67], v[74:75], v[66:67]
	v_pk_mul_f32 v[68:69], v[76:77], v[68:69]
	v_cvt_pk_bf16_f32 v70, v70, v71
	v_cvt_pk_bf16_f32 v71, v72, v73
	v_cvt_pk_bf16_f32 v72, v66, v67
	v_cvt_pk_bf16_f32 v73, v68, v69
	global_store_dwordx4 v[238:239], v[70:73], off sc0 sc1
	v_add_u32_e32 v153, 128, v152
	v_mad_i64_i32 v[236:237], s[0:1], v153, s46, v[234:235]
	v_pk_mul_f32 v[226:227], v[62:63], s[56:57] op_sel_hi:[1,0]
	v_pk_mul_f32 v[228:229], v[64:65], s[56:57] op_sel_hi:[1,0]
	v_pk_mul_f32 v[230:231], v[58:59], s[56:57] op_sel_hi:[1,0]
	v_pk_mul_f32 v[232:233], v[60:61], s[56:57] op_sel_hi:[1,0]
	v_exp_f32_e32 v226, v226
	v_exp_f32_e32 v227, v227
	v_exp_f32_e32 v228, v228
	v_exp_f32_e32 v229, v229
	v_exp_f32_e32 v230, v230
	v_exp_f32_e32 v231, v231
	v_exp_f32_e32 v232, v232
	v_exp_f32_e32 v233, v233
	v_pk_add_f32 v[226:227], v[226:227], 1.0 op_sel_hi:[1,0]
	v_pk_add_f32 v[228:229], v[228:229], 1.0 op_sel_hi:[1,0]
	v_pk_add_f32 v[230:231], v[230:231], 1.0 op_sel_hi:[1,0]
	v_pk_add_f32 v[232:233], v[232:233], 1.0 op_sel_hi:[1,0]
	v_rcp_f32_e32 v226, v226
	v_rcp_f32_e32 v227, v227
	v_rcp_f32_e32 v228, v228
	v_rcp_f32_e32 v229, v229
	v_rcp_f32_e32 v230, v230
	v_rcp_f32_e32 v231, v231
	v_rcp_f32_e32 v232, v232
	v_rcp_f32_e32 v233, v233
	v_pk_mul_f32 v[62:63], v[62:63], v[226:227]
	v_pk_mul_f32 v[64:65], v[64:65], v[228:229]
	v_pk_mul_f32 v[58:59], v[58:59], v[230:231]
	v_pk_mul_f32 v[60:61], v[60:61], v[232:233]
	v_pk_mul_f32 v[54:55], v[62:63], v[54:55]
	v_pk_mul_f32 v[56:57], v[64:65], v[56:57]
	v_pk_mul_f32 v[50:51], v[58:59], v[50:51]
	v_pk_mul_f32 v[52:53], v[60:61], v[52:53]
	v_cvt_pk_bf16_f32 v54, v54, v55
	v_cvt_pk_bf16_f32 v55, v56, v57
	v_cvt_pk_bf16_f32 v56, v50, v51
	v_cvt_pk_bf16_f32 v57, v52, v53
	global_store_dwordx4 v[236:237], v[54:57], off sc0 sc1
	v_add_u32_e32 v153, 144, v152
	v_mad_i64_i32 v[238:239], s[0:1], v153, s46, v[234:235]
	v_pk_mul_f32 v[226:227], v[46:47], s[56:57] op_sel_hi:[1,0]
	v_pk_mul_f32 v[228:229], v[48:49], s[56:57] op_sel_hi:[1,0]
	v_pk_mul_f32 v[230:231], v[42:43], s[56:57] op_sel_hi:[1,0]
	v_pk_mul_f32 v[232:233], v[44:45], s[56:57] op_sel_hi:[1,0]
	v_exp_f32_e32 v226, v226
	v_exp_f32_e32 v227, v227
	v_exp_f32_e32 v228, v228
	v_exp_f32_e32 v229, v229
	v_exp_f32_e32 v230, v230
	v_exp_f32_e32 v231, v231
	v_exp_f32_e32 v232, v232
	v_exp_f32_e32 v233, v233
	v_pk_add_f32 v[226:227], v[226:227], 1.0 op_sel_hi:[1,0]
	v_pk_add_f32 v[228:229], v[228:229], 1.0 op_sel_hi:[1,0]
	v_pk_add_f32 v[230:231], v[230:231], 1.0 op_sel_hi:[1,0]
	v_pk_add_f32 v[232:233], v[232:233], 1.0 op_sel_hi:[1,0]
	v_rcp_f32_e32 v226, v226
	v_rcp_f32_e32 v227, v227
	v_rcp_f32_e32 v228, v228
	v_rcp_f32_e32 v229, v229
	v_rcp_f32_e32 v230, v230
	v_rcp_f32_e32 v231, v231
	v_rcp_f32_e32 v232, v232
	v_rcp_f32_e32 v233, v233
	v_pk_mul_f32 v[46:47], v[46:47], v[226:227]
	v_pk_mul_f32 v[48:49], v[48:49], v[228:229]
	v_pk_mul_f32 v[42:43], v[42:43], v[230:231]
	v_pk_mul_f32 v[44:45], v[44:45], v[232:233]
	v_pk_mul_f32 v[38:39], v[46:47], v[38:39]
	v_pk_mul_f32 v[40:41], v[48:49], v[40:41]
	v_pk_mul_f32 v[34:35], v[42:43], v[34:35]
	v_pk_mul_f32 v[36:37], v[44:45], v[36:37]
	v_cvt_pk_bf16_f32 v38, v38, v39
	v_cvt_pk_bf16_f32 v39, v40, v41
	v_cvt_pk_bf16_f32 v40, v34, v35
	v_cvt_pk_bf16_f32 v41, v36, v37
	global_store_dwordx4 v[238:239], v[38:41], off sc0 sc1
	v_add_u32_e32 v153, 160, v152
	v_mad_i64_i32 v[236:237], s[0:1], v153, s46, v[234:235]
	v_pk_mul_f32 v[226:227], v[30:31], s[56:57] op_sel_hi:[1,0]
	v_pk_mul_f32 v[228:229], v[32:33], s[56:57] op_sel_hi:[1,0]
	v_pk_mul_f32 v[230:231], v[26:27], s[56:57] op_sel_hi:[1,0]
	v_pk_mul_f32 v[232:233], v[28:29], s[56:57] op_sel_hi:[1,0]
	v_exp_f32_e32 v226, v226
	v_exp_f32_e32 v227, v227
	v_exp_f32_e32 v228, v228
	v_exp_f32_e32 v229, v229
	v_exp_f32_e32 v230, v230
	v_exp_f32_e32 v231, v231
	v_exp_f32_e32 v232, v232
	v_exp_f32_e32 v233, v233
	v_pk_add_f32 v[226:227], v[226:227], 1.0 op_sel_hi:[1,0]
	v_pk_add_f32 v[228:229], v[228:229], 1.0 op_sel_hi:[1,0]
	v_pk_add_f32 v[230:231], v[230:231], 1.0 op_sel_hi:[1,0]
	v_pk_add_f32 v[232:233], v[232:233], 1.0 op_sel_hi:[1,0]
	v_rcp_f32_e32 v226, v226
	v_rcp_f32_e32 v227, v227
	v_rcp_f32_e32 v228, v228
	v_rcp_f32_e32 v229, v229
	v_rcp_f32_e32 v230, v230
	v_rcp_f32_e32 v231, v231
	v_rcp_f32_e32 v232, v232
	v_rcp_f32_e32 v233, v233
	v_pk_mul_f32 v[30:31], v[30:31], v[226:227]
	v_pk_mul_f32 v[32:33], v[32:33], v[228:229]
	v_pk_mul_f32 v[26:27], v[26:27], v[230:231]
	v_pk_mul_f32 v[28:29], v[28:29], v[232:233]
	v_pk_mul_f32 v[22:23], v[30:31], v[22:23]
	v_pk_mul_f32 v[24:25], v[32:33], v[24:25]
	v_pk_mul_f32 v[18:19], v[26:27], v[18:19]
	v_pk_mul_f32 v[20:21], v[28:29], v[20:21]
	v_cvt_pk_bf16_f32 v22, v22, v23
	v_cvt_pk_bf16_f32 v23, v24, v25
	v_cvt_pk_bf16_f32 v24, v18, v19
	v_cvt_pk_bf16_f32 v25, v20, v21
	global_store_dwordx4 v[236:237], v[22:25], off sc0 sc1
	v_add_u32_e32 v153, 176, v152
	v_mad_i64_i32 v[238:239], s[0:1], v153, s46, v[234:235]
	v_pk_mul_f32 v[226:227], v[14:15], s[56:57] op_sel_hi:[1,0]
	v_pk_mul_f32 v[228:229], v[16:17], s[56:57] op_sel_hi:[1,0]
	v_pk_mul_f32 v[230:231], v[10:11], s[56:57] op_sel_hi:[1,0]
	v_pk_mul_f32 v[232:233], v[12:13], s[56:57] op_sel_hi:[1,0]
	v_exp_f32_e32 v226, v226
	v_exp_f32_e32 v227, v227
	v_exp_f32_e32 v228, v228
	v_exp_f32_e32 v229, v229
	v_exp_f32_e32 v230, v230
	v_exp_f32_e32 v231, v231
	v_exp_f32_e32 v232, v232
	v_exp_f32_e32 v233, v233
	v_pk_add_f32 v[226:227], v[226:227], 1.0 op_sel_hi:[1,0]
	v_pk_add_f32 v[228:229], v[228:229], 1.0 op_sel_hi:[1,0]
	v_pk_add_f32 v[230:231], v[230:231], 1.0 op_sel_hi:[1,0]
	v_pk_add_f32 v[232:233], v[232:233], 1.0 op_sel_hi:[1,0]
	v_rcp_f32_e32 v226, v226
	v_rcp_f32_e32 v227, v227
	v_rcp_f32_e32 v228, v228
	v_rcp_f32_e32 v229, v229
	v_rcp_f32_e32 v230, v230
	v_rcp_f32_e32 v231, v231
	v_rcp_f32_e32 v232, v232
	v_rcp_f32_e32 v233, v233
	v_pk_mul_f32 v[14:15], v[14:15], v[226:227]
	v_pk_mul_f32 v[16:17], v[16:17], v[228:229]
	v_pk_mul_f32 v[10:11], v[10:11], v[230:231]
	v_pk_mul_f32 v[12:13], v[12:13], v[232:233]
	v_pk_mul_f32 v[6:7], v[14:15], v[6:7]
	v_pk_mul_f32 v[8:9], v[16:17], v[8:9]
	v_pk_mul_f32 v[2:3], v[10:11], v[2:3]
	v_pk_mul_f32 v[4:5], v[12:13], v[4:5]
	v_cvt_pk_bf16_f32 v6, v6, v7
	v_cvt_pk_bf16_f32 v7, v8, v9
	v_cvt_pk_bf16_f32 v8, v2, v3
	v_cvt_pk_bf16_f32 v9, v4, v5
	global_store_dwordx4 v[238:239], v[6:9], off sc0 sc1
	s_cbranch_vccz .LBB0_72
	s_waitcnt vmcnt(0)
	s_cmpk_gt_u32 s30, 0xff
	s_cbranch_scc1 .LBB0_79
	s_barrier

.Lgemm_epi1:
	v_lshl_add_u32 v198, s49, 8, v206
	v_lshl_or_b32 v194, s48, 8, v208
	v_ashrrev_i32_e32 v195, 31, v194
	v_ashrrev_i32_e32 v199, 31, v198
	v_lshl_add_u64 v[196:197], v[194:195], 2, s[12:13]
	v_lshlrev_b64 v[130:131], 12, v[198:199]
	v_lshl_add_u64 v[130:131], v[196:197], 0, v[130:131]
	global_load_dwordx4 v[214:217], v[130:131], off
	global_load_dwordx4 v[218:221], v[130:131], off offset:16
	global_load_dwordx4 v[222:225], v[130:131], off offset:512
	global_load_dwordx4 v[226:229], v[130:131], off offset:528
	v_or_b32_e32 v204, 16, v198
	v_or_b32_e32 v202, 32, v198
	v_or_b32_e32 v200, 48, v198
	v_ashrrev_i32_e32 v205, 31, v204
	v_ashrrev_i32_e32 v203, 31, v202
	v_ashrrev_i32_e32 v201, 31, v200
	v_lshlrev_b64 v[130:131], 12, v[204:205]
	v_lshlrev_b64 v[132:133], 12, v[202:203]
	v_lshlrev_b64 v[134:135], 12, v[200:201]
	v_lshl_add_u64 v[130:131], v[196:197], 0, v[130:131]
	v_lshl_add_u64 v[132:133], v[196:197], 0, v[132:133]
	v_lshl_add_u64 v[134:135], v[196:197], 0, v[134:135]
	global_load_dwordx4 v[170:173], v[130:131], off offset:16
	global_load_dwordx4 v[174:177], v[130:131], off
	global_load_dwordx4 v[162:165], v[130:131], off offset:528
	global_load_dwordx4 v[166:169], v[130:131], off offset:512
	global_load_dwordx4 v[154:157], v[132:133], off offset:16
	global_load_dwordx4 v[158:161], v[132:133], off
	global_load_dwordx4 v[146:149], v[132:133], off offset:528
	global_load_dwordx4 v[150:153], v[132:133], off offset:512
	global_load_dwordx4 v[138:141], v[134:135], off offset:16
	global_load_dwordx4 v[142:145], v[134:135], off
	s_nop 0
	global_load_dwordx4 v[130:133], v[134:135], off offset:528
	s_nop 0
	global_load_dwordx4 v[134:137], v[134:135], off offset:512
	v_and_b32_e32 v230, 64, v212
	v_xor_b32_e32 v213, 16, v212
	v_add_u32_e32 v233, 64, v230
	v_cmp_lt_i32_e32 vcc, v213, v233
	v_xor_b32_e32 v232, 32, v212
	v_lshlrev_b64 v[230:231], 11, v[198:199]
	v_cndmask_b32_e32 v213, v212, v213, vcc
	v_lshlrev_b32_e32 v213, 2, v213
	v_cmp_lt_i32_e32 vcc, v232, v233
	v_lshl_add_u64 v[230:231], s[68:69], 0, v[230:231]
	v_lshl_add_u64 v[230:231], v[194:195], 1, v[230:231]
	v_cndmask_b32_e32 v232, v212, v232, vcc
	s_waitcnt vmcnt(0)
	v_pk_fma_f32 v[126:127], v[126:127], 0.5, v[214:215] op_sel_hi:[1,0,1]
	v_pk_fma_f32 v[128:129], v[128:129], 0.5, v[216:217] op_sel_hi:[1,0,1]
	v_pk_fma_f32 v[118:119], v[118:119], 0.5, v[222:223] op_sel_hi:[1,0,1]
	v_pk_fma_f32 v[214:215], v[116:117], 0.5, v[228:229] op_sel_hi:[1,0,1]
	v_mul_f32_e32 v116, v127, v127
	v_mul_f32_e32 v117, v119, v119
	v_pk_fma_f32 v[120:121], v[120:121], 0.5, v[224:225] op_sel_hi:[1,0,1]
	v_fmac_f32_e32 v116, v126, v126
	v_fmac_f32_e32 v117, v118, v118
	v_fmac_f32_e32 v116, v128, v128
	v_fmac_f32_e32 v117, v120, v120
	v_pk_fma_f32 v[122:123], v[122:123], 0.5, v[218:219] op_sel_hi:[1,0,1]
	v_pk_fma_f32 v[216:217], v[114:115], 0.5, v[226:227] op_sel_hi:[1,0,1]
	v_fmac_f32_e32 v116, v129, v129
	v_fmac_f32_e32 v117, v121, v121
	v_fmac_f32_e32 v116, v122, v122
	v_fmac_f32_e32 v117, v216, v216
	v_pk_fma_f32 v[124:125], v[124:125], 0.5, v[220:221] op_sel_hi:[1,0,1]
	v_fmac_f32_e32 v116, v123, v123
	v_fmac_f32_e32 v117, v217, v217
	v_fmac_f32_e32 v116, v124, v124
	v_fmac_f32_e32 v117, v214, v214
	v_fmac_f32_e32 v116, v125, v125
	v_fmac_f32_e32 v117, v215, v215
	v_cvt_pk_bf16_f32 v114, v126, v127
	v_add_f32_e32 v126, v116, v117
	ds_bpermute_b32 v127, v213, v126
	v_cvt_pk_bf16_f32 v115, v128, v129
	v_cvt_pk_bf16_f32 v116, v122, v123
	v_cvt_pk_bf16_f32 v117, v124, v125
	global_store_dwordx4 v[230:231], v[114:117], off sc0 sc1
	v_lshlrev_b32_e32 v122, 2, v232
	v_cvt_pk_bf16_f32 v118, v118, v119
	s_waitcnt lgkmcnt(0)
	v_add_f32_e32 v114, v126, v127
	ds_bpermute_b32 v115, v122, v114
	v_cvt_pk_bf16_f32 v119, v120, v121
	v_cvt_pk_bf16_f32 v120, v216, v217
	v_cvt_pk_bf16_f32 v121, v214, v215
	global_store_dwordx4 v[230:231], v[118:121], off offset:256 sc0 sc1
	s_and_saveexec_b64 s[22:23], s[2:3]
	s_cbranch_execz .LBB0_122
	s_waitcnt lgkmcnt(0)
	v_add_f32_e32 v116, v114, v115
	v_lshl_add_u64 v[114:115], v[198:199], 2, s[14:15]
	global_atomic_add_f32 v[114:115], v116, off
.LBB0_122:
	s_or_b64 exec, exec, s[22:23]
	v_pk_fma_f32 v[110:111], v[110:111], 0.5, v[174:175] op_sel_hi:[1,0,1]
	v_pk_fma_f32 v[102:103], v[102:103], 0.5, v[166:167] op_sel_hi:[1,0,1]
	v_pk_fma_f32 v[124:125], v[98:99], 0.5, v[162:163] op_sel_hi:[1,0,1]
	v_mul_f32_e32 v98, v111, v111
	v_mul_f32_e32 v99, v103, v103
	v_pk_fma_f32 v[112:113], v[112:113], 0.5, v[176:177] op_sel_hi:[1,0,1]
	v_pk_fma_f32 v[104:105], v[104:105], 0.5, v[168:169] op_sel_hi:[1,0,1]
	v_fmac_f32_e32 v98, v110, v110
	v_fmac_f32_e32 v99, v102, v102
	v_fmac_f32_e32 v98, v112, v112
	v_fmac_f32_e32 v99, v104, v104
	v_pk_fma_f32 v[118:119], v[106:107], 0.5, v[170:171] op_sel_hi:[1,0,1]
	v_fmac_f32_e32 v98, v113, v113
	v_fmac_f32_e32 v99, v105, v105
	v_fmac_f32_e32 v98, v118, v118
	v_fmac_f32_e32 v99, v124, v124
	v_pk_fma_f32 v[116:117], v[108:109], 0.5, v[172:173] op_sel_hi:[1,0,1]
	v_pk_fma_f32 v[120:121], v[100:101], 0.5, v[164:165] op_sel_hi:[1,0,1]
	v_fmac_f32_e32 v98, v119, v119
	v_fmac_f32_e32 v99, v125, v125
	v_fmac_f32_e32 v98, v116, v116
	v_fmac_f32_e32 v99, v120, v120
	v_fmac_f32_e32 v98, v117, v117
	v_fmac_f32_e32 v99, v121, v121
	v_add_f32_e32 v101, v98, v99
	v_cvt_pk_bf16_f32 v107, v112, v113
	ds_bpermute_b32 v112, v213, v101
	s_waitcnt lgkmcnt(1)
	v_lshlrev_b64 v[114:115], 11, v[204:205]
	v_lshl_add_u64 v[98:99], s[68:69], 0, v[114:115]
	v_cvt_pk_bf16_f32 v106, v110, v111
	v_lshl_add_u64 v[110:111], v[194:195], 1, v[98:99]
	s_waitcnt lgkmcnt(0)
	v_add_f32_e32 v98, v101, v112
	ds_bpermute_b32 v99, v122, v98
	v_cvt_pk_bf16_f32 v108, v118, v119
	v_cvt_pk_bf16_f32 v109, v116, v117
	v_cvt_pk_bf16_f32 v100, v102, v103
	v_cvt_pk_bf16_f32 v101, v104, v105
	v_cvt_pk_bf16_f32 v102, v124, v125
	v_cvt_pk_bf16_f32 v103, v120, v121
	global_store_dwordx4 v[110:111], v[106:109], off sc0 sc1
	global_store_dwordx4 v[110:111], v[100:103], off offset:256 sc0 sc1
	s_and_saveexec_b64 s[22:23], s[2:3]
	s_cbranch_execz .LBB0_124
	s_waitcnt lgkmcnt(0)
	v_add_f32_e32 v100, v98, v99
	v_lshl_add_u64 v[98:99], v[204:205], 2, s[14:15]
	global_atomic_add_f32 v[98:99], v100, off
.LBB0_124:
	s_or_b64 exec, exec, s[22:23]
	v_pk_fma_f32 v[94:95], v[94:95], 0.5, v[158:159] op_sel_hi:[1,0,1]
	v_pk_fma_f32 v[86:87], v[86:87], 0.5, v[150:151] op_sel_hi:[1,0,1]
	v_pk_fma_f32 v[106:107], v[82:83], 0.5, v[146:147] op_sel_hi:[1,0,1]
	v_mul_f32_e32 v82, v95, v95
	v_mul_f32_e32 v83, v87, v87
	v_pk_fma_f32 v[96:97], v[96:97], 0.5, v[160:161] op_sel_hi:[1,0,1]
	v_pk_fma_f32 v[88:89], v[88:89], 0.5, v[152:153] op_sel_hi:[1,0,1]
	v_fmac_f32_e32 v82, v94, v94
	v_fmac_f32_e32 v83, v86, v86
	v_fmac_f32_e32 v82, v96, v96
	v_fmac_f32_e32 v83, v88, v88
	v_pk_fma_f32 v[102:103], v[90:91], 0.5, v[154:155] op_sel_hi:[1,0,1]
	v_fmac_f32_e32 v82, v97, v97
	v_fmac_f32_e32 v83, v89, v89
	v_fmac_f32_e32 v82, v102, v102
	v_fmac_f32_e32 v83, v106, v106
	v_pk_fma_f32 v[100:101], v[92:93], 0.5, v[156:157] op_sel_hi:[1,0,1]
	v_pk_fma_f32 v[104:105], v[84:85], 0.5, v[148:149] op_sel_hi:[1,0,1]
	v_fmac_f32_e32 v82, v103, v103
	v_fmac_f32_e32 v83, v107, v107
	v_fmac_f32_e32 v82, v100, v100
	v_fmac_f32_e32 v83, v104, v104
	v_fmac_f32_e32 v82, v101, v101
	v_fmac_f32_e32 v83, v105, v105
	v_add_f32_e32 v85, v82, v83
	v_cvt_pk_bf16_f32 v91, v96, v97
	ds_bpermute_b32 v96, v213, v85
	s_waitcnt lgkmcnt(1)
	v_lshlrev_b64 v[98:99], 11, v[202:203]
	v_lshl_add_u64 v[82:83], s[68:69], 0, v[98:99]
	v_cvt_pk_bf16_f32 v90, v94, v95
	v_lshl_add_u64 v[94:95], v[194:195], 1, v[82:83]
	s_waitcnt lgkmcnt(0)
	v_add_f32_e32 v82, v85, v96
	ds_bpermute_b32 v83, v122, v82
	v_cvt_pk_bf16_f32 v92, v102, v103
	v_cvt_pk_bf16_f32 v93, v100, v101
	v_cvt_pk_bf16_f32 v84, v86, v87
	v_cvt_pk_bf16_f32 v85, v88, v89
	v_cvt_pk_bf16_f32 v86, v106, v107
	v_cvt_pk_bf16_f32 v87, v104, v105
	global_store_dwordx4 v[94:95], v[90:93], off sc0 sc1
	global_store_dwordx4 v[94:95], v[84:87], off offset:256 sc0 sc1
	s_and_saveexec_b64 s[22:23], s[2:3]
	s_cbranch_execz .LBB0_126
	s_waitcnt lgkmcnt(0)
	v_add_f32_e32 v84, v82, v83
	v_lshl_add_u64 v[82:83], v[202:203], 2, s[14:15]
	global_atomic_add_f32 v[82:83], v84, off
.LBB0_126:
	s_or_b64 exec, exec, s[22:23]
	v_pk_fma_f32 v[78:79], v[78:79], 0.5, v[142:143] op_sel_hi:[1,0,1]
	v_pk_fma_f32 v[70:71], v[70:71], 0.5, v[134:135] op_sel_hi:[1,0,1]
	v_pk_fma_f32 v[90:91], v[66:67], 0.5, v[130:131] op_sel_hi:[1,0,1]
	v_mul_f32_e32 v66, v79, v79
	v_mul_f32_e32 v67, v71, v71
	v_pk_fma_f32 v[80:81], v[80:81], 0.5, v[144:145] op_sel_hi:[1,0,1]
	v_pk_fma_f32 v[72:73], v[72:73], 0.5, v[136:137] op_sel_hi:[1,0,1]
	v_fmac_f32_e32 v66, v78, v78
	v_fmac_f32_e32 v67, v70, v70
	v_fmac_f32_e32 v66, v80, v80
	v_fmac_f32_e32 v67, v72, v72
	v_pk_fma_f32 v[86:87], v[74:75], 0.5, v[138:139] op_sel_hi:[1,0,1]
	v_fmac_f32_e32 v66, v81, v81
	v_fmac_f32_e32 v67, v73, v73
	v_fmac_f32_e32 v66, v86, v86
	v_fmac_f32_e32 v67, v90, v90
	v_pk_fma_f32 v[84:85], v[76:77], 0.5, v[140:141] op_sel_hi:[1,0,1]
	v_pk_fma_f32 v[88:89], v[68:69], 0.5, v[132:133] op_sel_hi:[1,0,1]
	v_fmac_f32_e32 v66, v87, v87
	v_fmac_f32_e32 v67, v91, v91
	v_fmac_f32_e32 v66, v84, v84
	v_fmac_f32_e32 v67, v88, v88
	v_fmac_f32_e32 v66, v85, v85
	v_fmac_f32_e32 v67, v89, v89
	v_add_f32_e32 v69, v66, v67
	v_cvt_pk_bf16_f32 v75, v80, v81
	ds_bpermute_b32 v80, v213, v69
	s_waitcnt lgkmcnt(1)
	v_lshlrev_b64 v[82:83], 11, v[200:201]
	v_lshl_add_u64 v[66:67], s[68:69], 0, v[82:83]
	v_cvt_pk_bf16_f32 v74, v78, v79
	v_lshl_add_u64 v[78:79], v[194:195], 1, v[66:67]
	s_waitcnt lgkmcnt(0)
	v_add_f32_e32 v66, v69, v80
	ds_bpermute_b32 v67, v122, v66
	v_cvt_pk_bf16_f32 v76, v86, v87
	v_cvt_pk_bf16_f32 v77, v84, v85
	v_cvt_pk_bf16_f32 v68, v70, v71
	v_cvt_pk_bf16_f32 v69, v72, v73
	v_cvt_pk_bf16_f32 v70, v90, v91
	v_cvt_pk_bf16_f32 v71, v88, v89
	global_store_dwordx4 v[78:79], v[74:77], off sc0 sc1
	global_store_dwordx4 v[78:79], v[68:71], off offset:256 sc0 sc1
	s_and_saveexec_b64 s[22:23], s[2:3]
	s_cbranch_execz .LBB0_128
	s_waitcnt lgkmcnt(0)
	v_add_f32_e32 v68, v66, v67
	v_lshl_add_u64 v[66:67], v[200:201], 2, s[14:15]
	global_atomic_add_f32 v[66:67], v68, off
.LBB0_128:
	s_or_b64 exec, exec, s[22:23]
	v_add_u32_e32 v120, 0x80, v198
	v_ashrrev_i32_e32 v121, 31, v120
	s_waitcnt lgkmcnt(0)
	v_lshlrev_b64 v[66:67], 12, v[120:121]
	v_lshl_add_u64 v[66:67], v[196:197], 0, v[66:67]
	global_load_dwordx4 v[124:127], v[66:67], off
	global_load_dwordx4 v[128:131], v[66:67], off offset:16
	global_load_dwordx4 v[132:135], v[66:67], off offset:512
	global_load_dwordx4 v[136:139], v[66:67], off offset:528
	v_add_u32_e32 v118, 0x90, v198
	v_add_u32_e32 v116, 0xa0, v198
	v_add_u32_e32 v114, 0xb0, v198
	v_ashrrev_i32_e32 v119, 31, v118
	v_ashrrev_i32_e32 v117, 31, v116
	v_ashrrev_i32_e32 v115, 31, v114
	v_lshlrev_b64 v[66:67], 12, v[118:119]
	v_lshlrev_b64 v[68:69], 12, v[116:117]
	v_lshlrev_b64 v[70:71], 12, v[114:115]
	v_lshl_add_u64 v[66:67], v[196:197], 0, v[66:67]
	v_lshl_add_u64 v[68:69], v[196:197], 0, v[68:69]
	v_lshl_add_u64 v[70:71], v[196:197], 0, v[70:71]
	global_load_dwordx4 v[106:109], v[66:67], off offset:16
	global_load_dwordx4 v[110:113], v[66:67], off
	global_load_dwordx4 v[98:101], v[66:67], off offset:528
	global_load_dwordx4 v[102:105], v[66:67], off offset:512
	global_load_dwordx4 v[90:93], v[68:69], off offset:16
	global_load_dwordx4 v[94:97], v[68:69], off
	global_load_dwordx4 v[82:85], v[68:69], off offset:528
	global_load_dwordx4 v[86:89], v[68:69], off offset:512
	global_load_dwordx4 v[74:77], v[70:71], off offset:16
	global_load_dwordx4 v[78:81], v[70:71], off
	s_nop 0
	global_load_dwordx4 v[66:69], v[70:71], off offset:528
	s_nop 0
	global_load_dwordx4 v[70:73], v[70:71], off offset:512
	v_lshlrev_b64 v[140:141], 11, v[120:121]
	s_waitcnt vmcnt(15)
	v_pk_fma_f32 v[62:63], v[62:63], 0.5, v[124:125] op_sel_hi:[1,0,1]
	v_pk_fma_f32 v[64:65], v[64:65], 0.5, v[126:127] op_sel_hi:[1,0,1]
	s_waitcnt vmcnt(13)
	v_pk_fma_f32 v[54:55], v[54:55], 0.5, v[132:133] op_sel_hi:[1,0,1]
	s_waitcnt vmcnt(12)
	v_pk_fma_f32 v[126:127], v[50:51], 0.5, v[136:137] op_sel_hi:[1,0,1]
	v_cvt_pk_bf16_f32 v50, v62, v63
	v_mul_f32_e32 v63, v63, v63
	v_mul_f32_e32 v123, v55, v55
	v_pk_fma_f32 v[56:57], v[56:57], 0.5, v[134:135] op_sel_hi:[1,0,1]
	v_fmac_f32_e32 v63, v62, v62
	v_fmac_f32_e32 v123, v54, v54
	v_fmac_f32_e32 v63, v64, v64
	v_fmac_f32_e32 v123, v56, v56
	v_pk_fma_f32 v[58:59], v[58:59], 0.5, v[128:129] op_sel_hi:[1,0,1]
	v_fmac_f32_e32 v63, v65, v65
	v_fmac_f32_e32 v123, v57, v57
	v_fmac_f32_e32 v63, v58, v58
	v_fmac_f32_e32 v123, v126, v126
	v_pk_fma_f32 v[60:61], v[60:61], 0.5, v[130:131] op_sel_hi:[1,0,1]
	v_pk_fma_f32 v[124:125], v[52:53], 0.5, v[138:139] op_sel_hi:[1,0,1]
	v_fmac_f32_e32 v63, v59, v59
	v_fmac_f32_e32 v123, v127, v127
	v_fmac_f32_e32 v63, v60, v60
	v_fmac_f32_e32 v123, v124, v124
	v_fmac_f32_e32 v63, v61, v61
	v_fmac_f32_e32 v123, v125, v125
	v_cvt_pk_bf16_f32 v53, v60, v61
	v_add_f32_e32 v60, v63, v123
	ds_bpermute_b32 v61, v213, v60
	v_cvt_pk_bf16_f32 v52, v58, v59
	v_lshl_add_u64 v[58:59], s[68:69], 0, v[140:141]
	v_cvt_pk_bf16_f32 v51, v64, v65
	v_lshl_add_u64 v[58:59], v[194:195], 1, v[58:59]
	global_store_dwordx4 v[58:59], v[50:53], off sc0 sc1
	s_waitcnt lgkmcnt(0)
	s_nop 0
	v_add_f32_e32 v50, v60, v61
	ds_bpermute_b32 v51, v122, v50
	v_cvt_pk_bf16_f32 v52, v54, v55
	v_cvt_pk_bf16_f32 v53, v56, v57
	v_cvt_pk_bf16_f32 v54, v126, v127
	v_cvt_pk_bf16_f32 v55, v124, v125
	global_store_dwordx4 v[58:59], v[52:55], off offset:256 sc0 sc1
	s_and_saveexec_b64 s[22:23], s[2:3]
	s_cbranch_execz .LBB0_130
	s_waitcnt lgkmcnt(0)
	v_add_f32_e32 v52, v50, v51
	v_lshl_add_u64 v[50:51], v[120:121], 2, s[14:15]
	global_atomic_add_f32 v[50:51], v52, off
.LBB0_130:
	s_or_b64 exec, exec, s[22:23]
	s_waitcnt vmcnt(12)
	v_pk_fma_f32 v[46:47], v[46:47], 0.5, v[110:111] op_sel_hi:[1,0,1]
	s_waitcnt vmcnt(10)
	v_pk_fma_f32 v[38:39], v[38:39], 0.5, v[102:103] op_sel_hi:[1,0,1]
	v_pk_fma_f32 v[58:59], v[34:35], 0.5, v[98:99] op_sel_hi:[1,0,1]
	v_mul_f32_e32 v34, v47, v47
	v_mul_f32_e32 v35, v39, v39
	v_pk_fma_f32 v[48:49], v[48:49], 0.5, v[112:113] op_sel_hi:[1,0,1]
	v_pk_fma_f32 v[40:41], v[40:41], 0.5, v[104:105] op_sel_hi:[1,0,1]
	v_fmac_f32_e32 v34, v46, v46
	v_fmac_f32_e32 v35, v38, v38
	v_fmac_f32_e32 v34, v48, v48
	v_fmac_f32_e32 v35, v40, v40
	v_pk_fma_f32 v[54:55], v[42:43], 0.5, v[106:107] op_sel_hi:[1,0,1]
	v_fmac_f32_e32 v34, v49, v49
	v_fmac_f32_e32 v35, v41, v41
	v_fmac_f32_e32 v34, v54, v54
	v_fmac_f32_e32 v35, v58, v58
	v_pk_fma_f32 v[52:53], v[44:45], 0.5, v[108:109] op_sel_hi:[1,0,1]
	v_pk_fma_f32 v[56:57], v[36:37], 0.5, v[100:101] op_sel_hi:[1,0,1]
	v_fmac_f32_e32 v34, v55, v55
	v_fmac_f32_e32 v35, v59, v59
	v_fmac_f32_e32 v34, v52, v52
	v_fmac_f32_e32 v35, v56, v56
	v_fmac_f32_e32 v34, v53, v53
	v_fmac_f32_e32 v35, v57, v57
	v_add_f32_e32 v37, v34, v35
	v_cvt_pk_bf16_f32 v43, v48, v49
	ds_bpermute_b32 v48, v213, v37
	s_waitcnt lgkmcnt(1)
	v_lshlrev_b64 v[50:51], 11, v[118:119]
	v_lshl_add_u64 v[34:35], s[68:69], 0, v[50:51]
	v_cvt_pk_bf16_f32 v42, v46, v47
	v_lshl_add_u64 v[46:47], v[194:195], 1, v[34:35]
	s_waitcnt lgkmcnt(0)
	v_add_f32_e32 v34, v37, v48
	ds_bpermute_b32 v35, v122, v34
	v_cvt_pk_bf16_f32 v44, v54, v55
	v_cvt_pk_bf16_f32 v45, v52, v53
	v_cvt_pk_bf16_f32 v36, v38, v39
	v_cvt_pk_bf16_f32 v37, v40, v41
	v_cvt_pk_bf16_f32 v38, v58, v59
	v_cvt_pk_bf16_f32 v39, v56, v57
	global_store_dwordx4 v[46:47], v[42:45], off sc0 sc1
	global_store_dwordx4 v[46:47], v[36:39], off offset:256 sc0 sc1
	s_and_saveexec_b64 s[22:23], s[2:3]
	s_cbranch_execz .LBB0_132
	s_waitcnt lgkmcnt(0)
	v_add_f32_e32 v36, v34, v35
	v_lshl_add_u64 v[34:35], v[118:119], 2, s[14:15]
	global_atomic_add_f32 v[34:35], v36, off
.LBB0_132:
	s_or_b64 exec, exec, s[22:23]
	s_waitcnt vmcnt(10)
	v_pk_fma_f32 v[30:31], v[30:31], 0.5, v[94:95] op_sel_hi:[1,0,1]
	s_waitcnt vmcnt(8)
	v_pk_fma_f32 v[22:23], v[22:23], 0.5, v[86:87] op_sel_hi:[1,0,1]
	v_pk_fma_f32 v[42:43], v[18:19], 0.5, v[82:83] op_sel_hi:[1,0,1]
	v_mul_f32_e32 v18, v31, v31
	v_mul_f32_e32 v19, v23, v23
	v_pk_fma_f32 v[32:33], v[32:33], 0.5, v[96:97] op_sel_hi:[1,0,1]
	v_pk_fma_f32 v[24:25], v[24:25], 0.5, v[88:89] op_sel_hi:[1,0,1]
	v_fmac_f32_e32 v18, v30, v30
	v_fmac_f32_e32 v19, v22, v22
	v_fmac_f32_e32 v18, v32, v32
	v_fmac_f32_e32 v19, v24, v24
	v_pk_fma_f32 v[38:39], v[26:27], 0.5, v[90:91] op_sel_hi:[1,0,1]
	v_fmac_f32_e32 v18, v33, v33
	v_fmac_f32_e32 v19, v25, v25
	v_fmac_f32_e32 v18, v38, v38
	v_fmac_f32_e32 v19, v42, v42
	v_pk_fma_f32 v[36:37], v[28:29], 0.5, v[92:93] op_sel_hi:[1,0,1]
	v_pk_fma_f32 v[40:41], v[20:21], 0.5, v[84:85] op_sel_hi:[1,0,1]
	v_fmac_f32_e32 v18, v39, v39
	v_fmac_f32_e32 v19, v43, v43
	v_fmac_f32_e32 v18, v36, v36
	v_fmac_f32_e32 v19, v40, v40
	v_fmac_f32_e32 v18, v37, v37
	v_fmac_f32_e32 v19, v41, v41
	v_add_f32_e32 v21, v18, v19
	v_cvt_pk_bf16_f32 v27, v32, v33
	ds_bpermute_b32 v32, v213, v21
	s_waitcnt lgkmcnt(1)
	v_lshlrev_b64 v[34:35], 11, v[116:117]
	v_lshl_add_u64 v[18:19], s[68:69], 0, v[34:35]
	v_cvt_pk_bf16_f32 v26, v30, v31
	v_lshl_add_u64 v[30:31], v[194:195], 1, v[18:19]
	s_waitcnt lgkmcnt(0)
	v_add_f32_e32 v18, v21, v32
	ds_bpermute_b32 v19, v122, v18
	v_cvt_pk_bf16_f32 v28, v38, v39
	v_cvt_pk_bf16_f32 v29, v36, v37
	v_cvt_pk_bf16_f32 v20, v22, v23
	v_cvt_pk_bf16_f32 v21, v24, v25
	v_cvt_pk_bf16_f32 v22, v42, v43
	v_cvt_pk_bf16_f32 v23, v40, v41
	global_store_dwordx4 v[30:31], v[26:29], off sc0 sc1
	global_store_dwordx4 v[30:31], v[20:23], off offset:256 sc0 sc1
	s_and_saveexec_b64 s[22:23], s[2:3]
	s_cbranch_execz .LBB0_134
	s_waitcnt lgkmcnt(0)
	v_add_f32_e32 v20, v18, v19
	v_lshl_add_u64 v[18:19], v[116:117], 2, s[14:15]
	global_atomic_add_f32 v[18:19], v20, off
.LBB0_134:
	s_or_b64 exec, exec, s[22:23]
	s_waitcnt vmcnt(8)
	v_pk_fma_f32 v[14:15], v[14:15], 0.5, v[78:79] op_sel_hi:[1,0,1]
	s_waitcnt vmcnt(6)
	v_pk_fma_f32 v[6:7], v[6:7], 0.5, v[70:71] op_sel_hi:[1,0,1]
	v_pk_fma_f32 v[26:27], v[2:3], 0.5, v[66:67] op_sel_hi:[1,0,1]
	v_mul_f32_e32 v2, v15, v15
	v_mul_f32_e32 v3, v7, v7
	v_pk_fma_f32 v[16:17], v[16:17], 0.5, v[80:81] op_sel_hi:[1,0,1]
	v_pk_fma_f32 v[8:9], v[8:9], 0.5, v[72:73] op_sel_hi:[1,0,1]
	v_fmac_f32_e32 v2, v14, v14
	v_fmac_f32_e32 v3, v6, v6
	v_fmac_f32_e32 v2, v16, v16
	v_fmac_f32_e32 v3, v8, v8
	v_pk_fma_f32 v[22:23], v[10:11], 0.5, v[74:75] op_sel_hi:[1,0,1]
	v_fmac_f32_e32 v2, v17, v17
	v_fmac_f32_e32 v3, v9, v9
	v_fmac_f32_e32 v2, v22, v22
	v_fmac_f32_e32 v3, v26, v26
	v_pk_fma_f32 v[20:21], v[12:13], 0.5, v[76:77] op_sel_hi:[1,0,1]
	v_pk_fma_f32 v[24:25], v[4:5], 0.5, v[68:69] op_sel_hi:[1,0,1]
	v_fmac_f32_e32 v2, v23, v23
	v_fmac_f32_e32 v3, v27, v27
	v_fmac_f32_e32 v2, v20, v20
	v_fmac_f32_e32 v3, v24, v24
	v_fmac_f32_e32 v2, v21, v21
	v_fmac_f32_e32 v3, v25, v25
	v_add_f32_e32 v5, v2, v3
	v_cvt_pk_bf16_f32 v11, v16, v17
	ds_bpermute_b32 v16, v213, v5
	s_waitcnt lgkmcnt(1)
	v_lshlrev_b64 v[18:19], 11, v[114:115]
	v_lshl_add_u64 v[2:3], s[68:69], 0, v[18:19]
	v_cvt_pk_bf16_f32 v10, v14, v15
	v_lshl_add_u64 v[14:15], v[194:195], 1, v[2:3]
	s_waitcnt lgkmcnt(0)
	v_add_f32_e32 v2, v5, v16
	ds_bpermute_b32 v3, v122, v2
	v_cvt_pk_bf16_f32 v12, v22, v23
	v_cvt_pk_bf16_f32 v13, v20, v21
	v_cvt_pk_bf16_f32 v4, v6, v7
	v_cvt_pk_bf16_f32 v5, v8, v9
	v_cvt_pk_bf16_f32 v6, v26, v27
	v_cvt_pk_bf16_f32 v7, v24, v25
	global_store_dwordx4 v[14:15], v[10:13], off sc0 sc1
	global_store_dwordx4 v[14:15], v[4:7], off offset:256 sc0 sc1
	s_and_saveexec_b64 s[22:23], s[2:3]
	s_cbranch_execz .LBB0_107
	s_waitcnt lgkmcnt(0)
	v_add_f32_e32 v4, v2, v3
	v_lshl_add_u64 v[2:3], v[114:115], 2, s[14:15]
	global_atomic_add_f32 v[2:3], v4, off
	s_branch .LBB0_107

.LBB0_211:
	s_waitcnt lgkmcnt(0)
	v_pk_mul_f32 v[128:129], v[128:129], v[152:153] op_sel_hi:[1,0]
	v_pk_mul_f32 v[126:127], v[126:127], v[152:153] op_sel_hi:[1,0]
	v_pk_mul_f32 v[168:169], v[124:125], v[152:153] op_sel_hi:[1,0]
	v_pk_mul_f32 v[124:125], v[122:123], v[152:153] op_sel_hi:[1,0]
	v_cvt_pk_bf16_f32 v122, v126, v127
	v_cvt_pk_bf16_f32 v123, v128, v129
	v_cvt_pk_bf16_f32 v124, v124, v125
	v_cvt_pk_bf16_f32 v125, v168, v169
	global_store_dwordx4 v[158:159], v[122:125], off sc0 sc1
	s_andn2_b64 vcc, exec, s[34:35]
	s_nop 0
	v_cndmask_b32_e64 v122, 0, 1, s[34:35]
	v_cmp_ne_u32_e64 s[4:5], 1, v122
	s_mov_b64 s[34:35], -1
	s_cbranch_vccnz .LBB0_213
	v_mov_b32_e32 v138, v148
	v_lshl_add_u64 v[122:123], v[138:139], 1, v[154:155]
	v_lshl_add_u64 v[122:123], v[122:123], 0, s[22:23]
	s_mov_b64 s[34:35], 0

.LBB0_215:
	v_mov_b32_e32 v153, v152
	v_mov_b32_e32 v124, v152
	v_mov_b32_e32 v125, v152
	v_pk_mul_f32 v[120:121], v[120:121], v[124:125]
	v_pk_mul_f32 v[118:119], v[118:119], v[152:153]
	v_pk_mul_f32 v[124:125], v[116:117], v[124:125]
	v_pk_mul_f32 v[116:117], v[114:115], v[152:153]
	v_cvt_pk_bf16_f32 v114, v118, v119
	v_cvt_pk_bf16_f32 v115, v120, v121
	v_cvt_pk_bf16_f32 v116, v116, v117
	v_cvt_pk_bf16_f32 v117, v124, v125
	global_store_dwordx4 v[122:123], v[114:117], off sc0 sc1
	ds_read_b32 v114, v167 offset:64
	v_or_b32_e32 v118, 16, v150
	v_ashrrev_i32_e32 v119, 31, v118
	v_lshlrev_b64 v[116:117], 11, v[118:119]
	s_mov_b64 s[34:35], -1
	s_and_b64 vcc, exec, s[4:5]
	v_lshl_add_u64 v[116:117], s[8:9], 0, v[116:117]
	s_cbranch_vccnz .LBB0_217
	v_mov_b32_e32 v138, v148
	v_lshl_add_u64 v[120:121], v[138:139], 1, v[116:117]
	v_lshl_add_u64 v[120:121], v[120:121], 0, s[20:21]
	s_mov_b64 s[34:35], 0

.LBB0_219:
	s_waitcnt lgkmcnt(0)
	v_pk_mul_f32 v[112:113], v[112:113], v[114:115] op_sel_hi:[1,0]
	v_pk_mul_f32 v[110:111], v[110:111], v[114:115] op_sel_hi:[1,0]
	v_pk_mul_f32 v[122:123], v[108:109], v[114:115] op_sel_hi:[1,0]
	v_pk_mul_f32 v[108:109], v[106:107], v[114:115] op_sel_hi:[1,0]
	v_cvt_pk_bf16_f32 v106, v110, v111
	v_cvt_pk_bf16_f32 v107, v112, v113
	v_cvt_pk_bf16_f32 v108, v108, v109
	v_cvt_pk_bf16_f32 v109, v122, v123
	s_and_b64 vcc, exec, s[4:5]
	s_mov_b64 s[34:35], -1
	global_store_dwordx4 v[120:121], v[106:109], off sc0 sc1
	s_cbranch_vccnz .LBB0_221
	v_mov_b32_e32 v138, v148
	v_lshl_add_u64 v[106:107], v[138:139], 1, v[116:117]
	v_lshl_add_u64 v[106:107], v[106:107], 0, s[22:23]
	s_mov_b64 s[34:35], 0

.LBB0_223:
	v_mov_b32_e32 v115, v114
	v_mov_b32_e32 v108, v114
	v_mov_b32_e32 v109, v114
	v_pk_mul_f32 v[104:105], v[104:105], v[108:109]
	v_pk_mul_f32 v[102:103], v[102:103], v[114:115]
	v_pk_mul_f32 v[108:109], v[100:101], v[108:109]
	v_pk_mul_f32 v[100:101], v[98:99], v[114:115]
	v_cvt_pk_bf16_f32 v98, v102, v103
	v_cvt_pk_bf16_f32 v99, v104, v105
	v_cvt_pk_bf16_f32 v100, v100, v101
	v_cvt_pk_bf16_f32 v101, v108, v109
	global_store_dwordx4 v[106:107], v[98:101], off sc0 sc1
	ds_read_b32 v98, v167 offset:128
	v_or_b32_e32 v102, 32, v150
	v_ashrrev_i32_e32 v103, 31, v102
	v_lshlrev_b64 v[100:101], 11, v[102:103]
	s_mov_b64 s[34:35], -1
	s_and_b64 vcc, exec, s[4:5]
	v_lshl_add_u64 v[100:101], s[8:9], 0, v[100:101]
	s_cbranch_vccnz .LBB0_225
	v_mov_b32_e32 v138, v148
	v_lshl_add_u64 v[104:105], v[138:139], 1, v[100:101]
	v_lshl_add_u64 v[104:105], v[104:105], 0, s[20:21]
	s_mov_b64 s[34:35], 0

.LBB0_227:
	s_waitcnt lgkmcnt(0)
	v_pk_mul_f32 v[96:97], v[96:97], v[98:99] op_sel_hi:[1,0]
	v_pk_mul_f32 v[94:95], v[94:95], v[98:99] op_sel_hi:[1,0]
	v_pk_mul_f32 v[106:107], v[92:93], v[98:99] op_sel_hi:[1,0]
	v_pk_mul_f32 v[92:93], v[90:91], v[98:99] op_sel_hi:[1,0]
	v_cvt_pk_bf16_f32 v90, v94, v95
	v_cvt_pk_bf16_f32 v91, v96, v97
	v_cvt_pk_bf16_f32 v92, v92, v93
	v_cvt_pk_bf16_f32 v93, v106, v107
	s_and_b64 vcc, exec, s[4:5]
	s_mov_b64 s[34:35], -1
	global_store_dwordx4 v[104:105], v[90:93], off sc0 sc1
	s_cbranch_vccnz .LBB0_229
	v_mov_b32_e32 v138, v148
	v_lshl_add_u64 v[90:91], v[138:139], 1, v[100:101]
	v_lshl_add_u64 v[90:91], v[90:91], 0, s[22:23]
	s_mov_b64 s[34:35], 0

.LBB0_231:
	v_mov_b32_e32 v99, v98
	v_mov_b32_e32 v92, v98
	v_mov_b32_e32 v93, v98
	v_pk_mul_f32 v[88:89], v[88:89], v[92:93]
	v_pk_mul_f32 v[86:87], v[86:87], v[98:99]
	v_pk_mul_f32 v[92:93], v[84:85], v[92:93]
	v_pk_mul_f32 v[84:85], v[82:83], v[98:99]
	v_cvt_pk_bf16_f32 v82, v86, v87
	v_cvt_pk_bf16_f32 v83, v88, v89
	v_cvt_pk_bf16_f32 v84, v84, v85
	v_cvt_pk_bf16_f32 v85, v92, v93
	global_store_dwordx4 v[90:91], v[82:85], off sc0 sc1
	ds_read_b32 v82, v167 offset:192
	v_or_b32_e32 v86, 48, v150
	v_ashrrev_i32_e32 v87, 31, v86
	v_lshlrev_b64 v[84:85], 11, v[86:87]
	s_mov_b64 s[34:35], -1
	s_and_b64 vcc, exec, s[4:5]
	v_lshl_add_u64 v[84:85], s[8:9], 0, v[84:85]
	s_cbranch_vccnz .LBB0_233
	v_mov_b32_e32 v138, v148
	v_lshl_add_u64 v[88:89], v[138:139], 1, v[84:85]
	v_lshl_add_u64 v[88:89], v[88:89], 0, s[20:21]
	s_mov_b64 s[34:35], 0

.LBB0_235:
	s_waitcnt lgkmcnt(0)
	v_pk_mul_f32 v[80:81], v[80:81], v[82:83] op_sel_hi:[1,0]
	v_pk_mul_f32 v[78:79], v[78:79], v[82:83] op_sel_hi:[1,0]
	v_pk_mul_f32 v[90:91], v[76:77], v[82:83] op_sel_hi:[1,0]
	v_pk_mul_f32 v[76:77], v[74:75], v[82:83] op_sel_hi:[1,0]
	v_cvt_pk_bf16_f32 v74, v78, v79
	v_cvt_pk_bf16_f32 v75, v80, v81
	v_cvt_pk_bf16_f32 v76, v76, v77
	v_cvt_pk_bf16_f32 v77, v90, v91
	s_and_b64 vcc, exec, s[4:5]
	s_mov_b64 s[34:35], -1
	global_store_dwordx4 v[88:89], v[74:77], off sc0 sc1
	s_cbranch_vccnz .LBB0_237
	v_mov_b32_e32 v138, v148
	v_lshl_add_u64 v[74:75], v[138:139], 1, v[84:85]
	v_lshl_add_u64 v[74:75], v[74:75], 0, s[22:23]
	s_mov_b64 s[34:35], 0

.LBB0_239:
	v_mov_b32_e32 v83, v82
	v_mov_b32_e32 v76, v82
	v_mov_b32_e32 v77, v82
	v_pk_mul_f32 v[72:73], v[72:73], v[76:77]
	v_pk_mul_f32 v[70:71], v[70:71], v[82:83]
	v_pk_mul_f32 v[76:77], v[68:69], v[76:77]
	v_pk_mul_f32 v[68:69], v[66:67], v[82:83]
	v_cvt_pk_bf16_f32 v66, v70, v71
	v_cvt_pk_bf16_f32 v67, v72, v73
	v_cvt_pk_bf16_f32 v68, v68, v69
	v_cvt_pk_bf16_f32 v69, v76, v77
	global_store_dwordx4 v[74:75], v[66:69], off sc0 sc1
	ds_read_b32 v66, v167 offset:512
	v_add_u32_e32 v70, 0x80, v150
	v_ashrrev_i32_e32 v71, 31, v70
	v_lshlrev_b64 v[68:69], 11, v[70:71]
	s_mov_b64 s[34:35], -1
	s_and_b64 vcc, exec, s[4:5]
	v_lshl_add_u64 v[68:69], s[8:9], 0, v[68:69]
	s_cbranch_vccnz .LBB0_241
	v_mov_b32_e32 v138, v148
	v_lshl_add_u64 v[72:73], v[138:139], 1, v[68:69]
	v_lshl_add_u64 v[72:73], v[72:73], 0, s[20:21]
	s_mov_b64 s[34:35], 0

.LBB0_243:
	s_waitcnt lgkmcnt(0)
	v_pk_mul_f32 v[64:65], v[64:65], v[66:67] op_sel_hi:[1,0]
	v_pk_mul_f32 v[62:63], v[62:63], v[66:67] op_sel_hi:[1,0]
	v_pk_mul_f32 v[74:75], v[60:61], v[66:67] op_sel_hi:[1,0]
	v_pk_mul_f32 v[60:61], v[58:59], v[66:67] op_sel_hi:[1,0]
	v_cvt_pk_bf16_f32 v58, v62, v63
	v_cvt_pk_bf16_f32 v59, v64, v65
	v_cvt_pk_bf16_f32 v60, v60, v61
	v_cvt_pk_bf16_f32 v61, v74, v75
	s_and_b64 vcc, exec, s[4:5]
	s_mov_b64 s[34:35], -1
	global_store_dwordx4 v[72:73], v[58:61], off sc0 sc1
	s_cbranch_vccnz .LBB0_245
	v_mov_b32_e32 v138, v148
	v_lshl_add_u64 v[58:59], v[138:139], 1, v[68:69]
	v_lshl_add_u64 v[58:59], v[58:59], 0, s[22:23]
	s_mov_b64 s[34:35], 0

.LBB0_247:
	v_mov_b32_e32 v67, v66
	v_mov_b32_e32 v60, v66
	v_mov_b32_e32 v61, v66
	v_pk_mul_f32 v[56:57], v[56:57], v[60:61]
	v_pk_mul_f32 v[54:55], v[54:55], v[66:67]
	v_pk_mul_f32 v[60:61], v[52:53], v[60:61]
	v_pk_mul_f32 v[52:53], v[50:51], v[66:67]
	v_cvt_pk_bf16_f32 v50, v54, v55
	v_cvt_pk_bf16_f32 v51, v56, v57
	v_cvt_pk_bf16_f32 v52, v52, v53
	v_cvt_pk_bf16_f32 v53, v60, v61
	global_store_dwordx4 v[58:59], v[50:53], off sc0 sc1
	ds_read_b32 v50, v167 offset:576
	v_add_u32_e32 v54, 0x90, v150
	v_ashrrev_i32_e32 v55, 31, v54
	v_lshlrev_b64 v[52:53], 11, v[54:55]
	s_mov_b64 s[34:35], -1
	s_and_b64 vcc, exec, s[4:5]
	v_lshl_add_u64 v[52:53], s[8:9], 0, v[52:53]
	s_cbranch_vccnz .LBB0_249
	v_mov_b32_e32 v138, v148
	v_lshl_add_u64 v[56:57], v[138:139], 1, v[52:53]
	v_lshl_add_u64 v[56:57], v[56:57], 0, s[20:21]
	s_mov_b64 s[34:35], 0

.LBB0_251:
	s_waitcnt lgkmcnt(0)
	v_pk_mul_f32 v[48:49], v[48:49], v[50:51] op_sel_hi:[1,0]
	v_pk_mul_f32 v[46:47], v[46:47], v[50:51] op_sel_hi:[1,0]
	v_pk_mul_f32 v[58:59], v[44:45], v[50:51] op_sel_hi:[1,0]
	v_pk_mul_f32 v[44:45], v[42:43], v[50:51] op_sel_hi:[1,0]
	v_cvt_pk_bf16_f32 v42, v46, v47
	v_cvt_pk_bf16_f32 v43, v48, v49
	v_cvt_pk_bf16_f32 v44, v44, v45
	v_cvt_pk_bf16_f32 v45, v58, v59
	s_and_b64 vcc, exec, s[4:5]
	s_mov_b64 s[34:35], -1
	global_store_dwordx4 v[56:57], v[42:45], off sc0 sc1
	s_cbranch_vccnz .LBB0_253
	v_mov_b32_e32 v138, v148
	v_lshl_add_u64 v[42:43], v[138:139], 1, v[52:53]
	v_lshl_add_u64 v[42:43], v[42:43], 0, s[22:23]
	s_mov_b64 s[34:35], 0

.LBB0_255:
	v_mov_b32_e32 v51, v50
	v_mov_b32_e32 v44, v50
	v_mov_b32_e32 v45, v50
	v_pk_mul_f32 v[40:41], v[40:41], v[44:45]
	v_pk_mul_f32 v[38:39], v[38:39], v[50:51]
	v_pk_mul_f32 v[44:45], v[36:37], v[44:45]
	v_pk_mul_f32 v[36:37], v[34:35], v[50:51]
	v_cvt_pk_bf16_f32 v34, v38, v39
	v_cvt_pk_bf16_f32 v35, v40, v41
	v_cvt_pk_bf16_f32 v36, v36, v37
	v_cvt_pk_bf16_f32 v37, v44, v45
	global_store_dwordx4 v[42:43], v[34:37], off sc0 sc1
	ds_read_b32 v34, v167 offset:640
	v_add_u32_e32 v38, 0xa0, v150
	v_ashrrev_i32_e32 v39, 31, v38
	v_lshlrev_b64 v[36:37], 11, v[38:39]
	s_mov_b64 s[34:35], -1
	s_and_b64 vcc, exec, s[4:5]
	v_lshl_add_u64 v[36:37], s[8:9], 0, v[36:37]
	s_cbranch_vccnz .LBB0_257
	v_mov_b32_e32 v138, v148
	v_lshl_add_u64 v[40:41], v[138:139], 1, v[36:37]
	v_lshl_add_u64 v[40:41], v[40:41], 0, s[20:21]
	s_mov_b64 s[34:35], 0

.LBB0_259:
	s_waitcnt lgkmcnt(0)
	v_pk_mul_f32 v[32:33], v[32:33], v[34:35] op_sel_hi:[1,0]
	v_pk_mul_f32 v[30:31], v[30:31], v[34:35] op_sel_hi:[1,0]
	v_pk_mul_f32 v[42:43], v[28:29], v[34:35] op_sel_hi:[1,0]
	v_pk_mul_f32 v[28:29], v[26:27], v[34:35] op_sel_hi:[1,0]
	v_cvt_pk_bf16_f32 v26, v30, v31
	v_cvt_pk_bf16_f32 v27, v32, v33
	v_cvt_pk_bf16_f32 v28, v28, v29
	v_cvt_pk_bf16_f32 v29, v42, v43
	s_and_b64 vcc, exec, s[4:5]
	s_mov_b64 s[34:35], -1
	global_store_dwordx4 v[40:41], v[26:29], off sc0 sc1
	s_cbranch_vccnz .LBB0_261
	v_mov_b32_e32 v138, v148
	v_lshl_add_u64 v[26:27], v[138:139], 1, v[36:37]
	v_lshl_add_u64 v[26:27], v[26:27], 0, s[22:23]
	s_mov_b64 s[34:35], 0

.LBB0_263:
	v_mov_b32_e32 v35, v34
	v_mov_b32_e32 v28, v34
	v_mov_b32_e32 v29, v34
	v_pk_mul_f32 v[24:25], v[24:25], v[28:29]
	v_pk_mul_f32 v[22:23], v[22:23], v[34:35]
	v_pk_mul_f32 v[28:29], v[20:21], v[28:29]
	v_pk_mul_f32 v[20:21], v[18:19], v[34:35]
	v_cvt_pk_bf16_f32 v18, v22, v23
	v_cvt_pk_bf16_f32 v19, v24, v25
	v_cvt_pk_bf16_f32 v20, v20, v21
	v_cvt_pk_bf16_f32 v21, v28, v29
	global_store_dwordx4 v[26:27], v[18:21], off sc0 sc1
	ds_read_b32 v18, v167 offset:704
	v_add_u32_e32 v22, 0xb0, v150
	v_ashrrev_i32_e32 v23, 31, v22
	v_lshlrev_b64 v[20:21], 11, v[22:23]
	s_mov_b64 s[34:35], -1
	s_and_b64 vcc, exec, s[4:5]
	v_lshl_add_u64 v[20:21], s[8:9], 0, v[20:21]
	s_cbranch_vccnz .LBB0_265
	v_mov_b32_e32 v138, v148
	v_lshl_add_u64 v[24:25], v[138:139], 1, v[20:21]
	v_lshl_add_u64 v[24:25], v[24:25], 0, s[20:21]
	s_mov_b64 s[34:35], 0

.LBB0_267:
	s_waitcnt lgkmcnt(0)
	v_pk_mul_f32 v[16:17], v[16:17], v[18:19] op_sel_hi:[1,0]
	v_pk_mul_f32 v[14:15], v[14:15], v[18:19] op_sel_hi:[1,0]
	v_pk_mul_f32 v[26:27], v[12:13], v[18:19] op_sel_hi:[1,0]
	v_pk_mul_f32 v[12:13], v[10:11], v[18:19] op_sel_hi:[1,0]
	v_cvt_pk_bf16_f32 v10, v14, v15
	v_cvt_pk_bf16_f32 v11, v16, v17
	v_cvt_pk_bf16_f32 v12, v12, v13
	v_cvt_pk_bf16_f32 v13, v26, v27
	s_and_b64 vcc, exec, s[4:5]
	s_mov_b64 s[4:5], -1
	global_store_dwordx4 v[24:25], v[10:13], off sc0 sc1
	s_cbranch_vccnz .LBB0_269
	v_mov_b32_e32 v138, v148
	v_lshl_add_u64 v[10:11], v[138:139], 1, v[20:21]
	v_lshl_add_u64 v[10:11], v[10:11], 0, s[22:23]
	s_mov_b64 s[4:5], 0

.Lgemm_epi3:
	v_lshl_or_b32 v170, s22, 8, v190
	v_lshl_add_u32 v174, s20, 8, v188
	v_ashrrev_i32_e32 v171, 31, v170
	v_lshlrev_b64 v[204:205], 1, v[170:171]
	v_ashrrev_i32_e32 v175, 31, v174
	v_lshl_add_u64 v[172:173], s[68:69], 0, v[204:205]
	v_lshlrev_b64 v[206:207], 11, v[174:175]
	v_lshl_add_u64 v[130:131], v[172:173], 0, v[206:207]
	global_load_dwordx4 v[196:199], v[130:131], off
	global_load_dwordx4 v[200:203], v[130:131], off offset:256
	v_or_b32_e32 v184, 16, v174
	v_or_b32_e32 v180, 32, v174
	v_or_b32_e32 v176, 48, v174
	v_ashrrev_i32_e32 v185, 31, v184
	v_ashrrev_i32_e32 v181, 31, v180
	v_ashrrev_i32_e32 v177, 31, v176
	v_lshlrev_b64 v[186:187], 11, v[184:185]
	v_lshlrev_b64 v[182:183], 11, v[180:181]
	v_lshlrev_b64 v[178:179], 11, v[176:177]
	v_lshl_add_u64 v[130:131], v[172:173], 0, v[186:187]
	v_lshl_add_u64 v[132:133], v[172:173], 0, v[182:183]
	v_lshl_add_u64 v[208:209], v[172:173], 0, v[178:179]
	global_load_dwordx4 v[150:153], v[130:131], off
	global_load_dwordx4 v[146:149], v[130:131], off offset:256
	global_load_dwordx4 v[142:145], v[132:133], off
	global_load_dwordx4 v[138:141], v[132:133], off offset:256
	global_load_dwordx4 v[134:137], v[208:209], off
	s_nop 0
	global_load_dwordx4 v[130:133], v[208:209], off offset:256
	v_lshl_add_u64 v[206:207], s[68:69], 0, v[206:207]
	v_and_b32_e32 v208, 64, v194
	v_lshl_add_u64 v[204:205], v[206:207], 0, v[204:205]
	v_xor_b32_e32 v195, 16, v194
	v_add_u32_e32 v208, 64, v208
	v_xor_b32_e32 v209, 32, v194
	v_cmp_lt_i32_e32 vcc, v195, v208
	s_waitcnt vmcnt(0)
	v_lshlrev_b32_e32 v206, 16, v196
	v_and_b32_e32 v207, 0xffff0000, v196
	v_lshlrev_b32_e32 v210, 16, v200
	v_and_b32_e32 v211, 0xffff0000, v200
	v_lshlrev_b32_e32 v196, 16, v197
	v_and_b32_e32 v197, 0xffff0000, v197
	v_lshlrev_b32_e32 v212, 16, v202
	v_and_b32_e32 v213, 0xffff0000, v202
	v_lshlrev_b32_e32 v202, 16, v203
	v_and_b32_e32 v203, 0xffff0000, v203
	v_pk_add_f32 v[126:127], v[126:127], v[206:207]
	v_pk_add_f32 v[118:119], v[118:119], v[210:211]
	v_lshlrev_b32_e32 v200, 16, v201
	v_and_b32_e32 v201, 0xffff0000, v201
	v_pk_add_f32 v[128:129], v[128:129], v[196:197]
	v_pk_add_f32 v[196:197], v[116:117], v[202:203]
	v_mul_f32_e32 v116, v127, v127
	v_mul_f32_e32 v117, v119, v119
	v_cndmask_b32_e32 v195, v194, v195, vcc
	v_cmp_lt_i32_e32 vcc, v209, v208
	v_pk_add_f32 v[120:121], v[120:121], v[200:201]
	v_fmac_f32_e32 v116, v126, v126
	v_fmac_f32_e32 v117, v118, v118
	v_cndmask_b32_e32 v214, v194, v209, vcc
	v_lshlrev_b32_e32 v208, 16, v198
	v_and_b32_e32 v209, 0xffff0000, v198
	v_lshlrev_b32_e32 v198, 16, v199
	v_and_b32_e32 v199, 0xffff0000, v199
	v_fmac_f32_e32 v116, v128, v128
	v_fmac_f32_e32 v117, v120, v120
	v_pk_add_f32 v[124:125], v[124:125], v[198:199]
	v_pk_add_f32 v[122:123], v[122:123], v[208:209]
	v_pk_add_f32 v[198:199], v[114:115], v[212:213]
	v_fmac_f32_e32 v116, v129, v129
	v_fmac_f32_e32 v117, v121, v121
	v_fmac_f32_e32 v116, v122, v122
	v_fmac_f32_e32 v117, v198, v198
	v_fmac_f32_e32 v116, v123, v123
	v_fmac_f32_e32 v117, v199, v199
	v_fmac_f32_e32 v116, v124, v124
	v_fmac_f32_e32 v117, v196, v196
	v_fmac_f32_e32 v116, v125, v125
	v_fmac_f32_e32 v117, v197, v197
	v_lshlrev_b32_e32 v195, 2, v195
	v_cvt_pk_bf16_f32 v114, v126, v127
	v_add_f32_e32 v126, v116, v117
	ds_bpermute_b32 v127, v195, v126
	v_cvt_pk_bf16_f32 v115, v128, v129
	v_cvt_pk_bf16_f32 v116, v122, v123
	v_cvt_pk_bf16_f32 v117, v124, v125
	global_store_dwordx4 v[204:205], v[114:117], off sc0 sc1
	v_cvt_pk_bf16_f32 v118, v118, v119
	v_cvt_pk_bf16_f32 v119, v120, v121
	s_waitcnt lgkmcnt(0)
	v_add_f32_e32 v115, v126, v127
	v_lshlrev_b32_e32 v114, 2, v214
	ds_bpermute_b32 v116, v114, v115
	v_cvt_pk_bf16_f32 v120, v198, v199
	v_cvt_pk_bf16_f32 v121, v196, v197
	global_store_dwordx4 v[204:205], v[118:121], off offset:256 sc0 sc1
	s_and_saveexec_b64 s[20:21], s[2:3]
	s_cbranch_execz .LBB0_589
	s_waitcnt lgkmcnt(0)
	v_add_f32_e32 v115, v115, v116
	v_lshl_add_u64 v[116:117], v[174:175], 2, s[6:7]
	global_atomic_add_f32 v[116:117], v115, off
.LBB0_589:
	s_or_b64 exec, exec, s[20:21]
	v_lshlrev_b32_e32 v118, 16, v151
	v_and_b32_e32 v119, 0xffff0000, v151
	v_lshlrev_b32_e32 v120, 16, v152
	v_and_b32_e32 v121, 0xffff0000, v152
	s_waitcnt lgkmcnt(0)
	v_lshlrev_b32_e32 v116, 16, v150
	v_and_b32_e32 v117, 0xffff0000, v150
	v_lshlrev_b32_e32 v122, 16, v153
	v_and_b32_e32 v123, 0xffff0000, v153
	v_pk_add_f32 v[112:113], v[112:113], v[118:119]
	v_pk_add_f32 v[118:119], v[106:107], v[120:121]
	v_lshlrev_b32_e32 v120, 16, v146
	v_and_b32_e32 v121, 0xffff0000, v146
	v_pk_add_f32 v[110:111], v[110:111], v[116:117]
	v_pk_add_f32 v[116:117], v[108:109], v[122:123]
	v_lshlrev_b32_e32 v122, 16, v147
	v_and_b32_e32 v123, 0xffff0000, v147
	v_lshlrev_b32_e32 v124, 16, v148
	v_and_b32_e32 v125, 0xffff0000, v148
	v_pk_add_f32 v[102:103], v[102:103], v[120:121]
	v_pk_add_f32 v[104:105], v[104:105], v[122:123]
	v_pk_add_f32 v[122:123], v[98:99], v[124:125]
	v_mul_f32_e32 v98, v111, v111
	v_mul_f32_e32 v99, v103, v103
	v_fmac_f32_e32 v98, v110, v110
	v_fmac_f32_e32 v99, v102, v102
	v_fmac_f32_e32 v98, v112, v112
	v_fmac_f32_e32 v99, v104, v104
	v_fmac_f32_e32 v98, v113, v113
	v_fmac_f32_e32 v99, v105, v105
	v_lshlrev_b32_e32 v126, 16, v149
	v_and_b32_e32 v127, 0xffff0000, v149
	v_fmac_f32_e32 v98, v118, v118
	v_fmac_f32_e32 v99, v122, v122
	v_pk_add_f32 v[120:121], v[100:101], v[126:127]
	v_fmac_f32_e32 v98, v119, v119
	v_fmac_f32_e32 v99, v123, v123
	v_fmac_f32_e32 v98, v116, v116
	v_fmac_f32_e32 v99, v120, v120
	v_fmac_f32_e32 v98, v117, v117
	v_fmac_f32_e32 v99, v121, v121
	v_add_f32_e32 v101, v98, v99
	v_cvt_pk_bf16_f32 v107, v112, v113
	ds_bpermute_b32 v112, v195, v101
	v_lshl_add_u64 v[98:99], s[68:69], 0, v[186:187]
	v_cvt_pk_bf16_f32 v106, v110, v111
	v_lshl_add_u64 v[110:111], v[170:171], 1, v[98:99]
	v_cvt_pk_bf16_f32 v108, v118, v119
	s_waitcnt lgkmcnt(0)
	v_add_f32_e32 v98, v101, v112
	ds_bpermute_b32 v99, v114, v98
	v_cvt_pk_bf16_f32 v109, v116, v117
	v_cvt_pk_bf16_f32 v100, v102, v103
	v_cvt_pk_bf16_f32 v101, v104, v105
	v_cvt_pk_bf16_f32 v102, v122, v123
	v_cvt_pk_bf16_f32 v103, v120, v121
	global_store_dwordx4 v[110:111], v[106:109], off sc0 sc1
	global_store_dwordx4 v[110:111], v[100:103], off offset:256 sc0 sc1
	s_and_saveexec_b64 s[20:21], s[2:3]
	s_cbranch_execz .LBB0_591
	s_waitcnt lgkmcnt(0)
	v_add_f32_e32 v100, v98, v99
	v_lshl_add_u64 v[98:99], v[184:185], 2, s[6:7]
	global_atomic_add_f32 v[98:99], v100, off
.LBB0_591:
	s_or_b64 exec, exec, s[20:21]
	v_lshlrev_b32_e32 v100, 16, v143
	v_and_b32_e32 v101, 0xffff0000, v143
	v_lshlrev_b32_e32 v102, 16, v144
	v_and_b32_e32 v103, 0xffff0000, v144
	v_lshlrev_b32_e32 v98, 16, v142
	s_waitcnt lgkmcnt(0)
	v_and_b32_e32 v99, 0xffff0000, v142
	v_lshlrev_b32_e32 v104, 16, v145
	v_and_b32_e32 v105, 0xffff0000, v145
	v_pk_add_f32 v[96:97], v[96:97], v[100:101]
	v_pk_add_f32 v[100:101], v[90:91], v[102:103]
	v_lshlrev_b32_e32 v102, 16, v138
	v_and_b32_e32 v103, 0xffff0000, v138
	v_pk_add_f32 v[94:95], v[94:95], v[98:99]
	v_pk_add_f32 v[98:99], v[92:93], v[104:105]
	v_lshlrev_b32_e32 v104, 16, v139
	v_and_b32_e32 v105, 0xffff0000, v139
	v_lshlrev_b32_e32 v106, 16, v140
	v_and_b32_e32 v107, 0xffff0000, v140
	v_pk_add_f32 v[86:87], v[86:87], v[102:103]
	v_pk_add_f32 v[88:89], v[88:89], v[104:105]
	v_pk_add_f32 v[104:105], v[82:83], v[106:107]
	v_mul_f32_e32 v82, v95, v95
	v_mul_f32_e32 v83, v87, v87
	v_fmac_f32_e32 v82, v94, v94
	v_fmac_f32_e32 v83, v86, v86
	v_fmac_f32_e32 v82, v96, v96
	v_fmac_f32_e32 v83, v88, v88
	v_fmac_f32_e32 v82, v97, v97
	v_fmac_f32_e32 v83, v89, v89
	v_lshlrev_b32_e32 v108, 16, v141
	v_and_b32_e32 v109, 0xffff0000, v141
	v_fmac_f32_e32 v82, v100, v100
	v_fmac_f32_e32 v83, v104, v104
	v_pk_add_f32 v[102:103], v[84:85], v[108:109]
	v_fmac_f32_e32 v82, v101, v101
	v_fmac_f32_e32 v83, v105, v105
	v_fmac_f32_e32 v82, v98, v98
	v_fmac_f32_e32 v83, v102, v102
	v_fmac_f32_e32 v82, v99, v99
	v_fmac_f32_e32 v83, v103, v103
	v_add_f32_e32 v85, v82, v83
	v_cvt_pk_bf16_f32 v91, v96, v97
	ds_bpermute_b32 v96, v195, v85
	v_lshl_add_u64 v[82:83], s[68:69], 0, v[182:183]
	v_cvt_pk_bf16_f32 v90, v94, v95
	v_lshl_add_u64 v[94:95], v[170:171], 1, v[82:83]
	v_cvt_pk_bf16_f32 v92, v100, v101
	s_waitcnt lgkmcnt(0)
	v_add_f32_e32 v82, v85, v96
	ds_bpermute_b32 v83, v114, v82
	v_cvt_pk_bf16_f32 v93, v98, v99
	v_cvt_pk_bf16_f32 v84, v86, v87
	v_cvt_pk_bf16_f32 v85, v88, v89
	v_cvt_pk_bf16_f32 v86, v104, v105
	v_cvt_pk_bf16_f32 v87, v102, v103
	global_store_dwordx4 v[94:95], v[90:93], off sc0 sc1
	global_store_dwordx4 v[94:95], v[84:87], off offset:256 sc0 sc1
	s_and_saveexec_b64 s[20:21], s[2:3]
	s_cbranch_execz .LBB0_593
	s_waitcnt lgkmcnt(0)
	v_add_f32_e32 v84, v82, v83
	v_lshl_add_u64 v[82:83], v[180:181], 2, s[6:7]
	global_atomic_add_f32 v[82:83], v84, off
.LBB0_593:
	s_or_b64 exec, exec, s[20:21]
	v_lshlrev_b32_e32 v84, 16, v135
	v_and_b32_e32 v85, 0xffff0000, v135
	v_lshlrev_b32_e32 v86, 16, v136
	v_and_b32_e32 v87, 0xffff0000, v136
	v_lshlrev_b32_e32 v82, 16, v134
	s_waitcnt lgkmcnt(0)
	v_and_b32_e32 v83, 0xffff0000, v134
	v_lshlrev_b32_e32 v88, 16, v137
	v_and_b32_e32 v89, 0xffff0000, v137
	v_pk_add_f32 v[80:81], v[80:81], v[84:85]
	v_pk_add_f32 v[84:85], v[74:75], v[86:87]
	v_lshlrev_b32_e32 v86, 16, v130
	v_and_b32_e32 v87, 0xffff0000, v130
	v_pk_add_f32 v[78:79], v[78:79], v[82:83]
	v_pk_add_f32 v[82:83], v[76:77], v[88:89]
	v_lshlrev_b32_e32 v88, 16, v131
	v_and_b32_e32 v89, 0xffff0000, v131
	v_lshlrev_b32_e32 v90, 16, v132
	v_and_b32_e32 v91, 0xffff0000, v132
	v_pk_add_f32 v[70:71], v[70:71], v[86:87]
	v_pk_add_f32 v[72:73], v[72:73], v[88:89]
	v_pk_add_f32 v[88:89], v[66:67], v[90:91]
	v_mul_f32_e32 v66, v79, v79
	v_mul_f32_e32 v67, v71, v71
	v_fmac_f32_e32 v66, v78, v78
	v_fmac_f32_e32 v67, v70, v70
	v_fmac_f32_e32 v66, v80, v80
	v_fmac_f32_e32 v67, v72, v72
	v_fmac_f32_e32 v66, v81, v81
	v_fmac_f32_e32 v67, v73, v73
	v_lshlrev_b32_e32 v92, 16, v133
	v_and_b32_e32 v93, 0xffff0000, v133
	v_fmac_f32_e32 v66, v84, v84
	v_fmac_f32_e32 v67, v88, v88
	v_pk_add_f32 v[86:87], v[68:69], v[92:93]
	v_fmac_f32_e32 v66, v85, v85
	v_fmac_f32_e32 v67, v89, v89
	v_fmac_f32_e32 v66, v82, v82
	v_fmac_f32_e32 v67, v86, v86
	v_fmac_f32_e32 v66, v83, v83
	v_fmac_f32_e32 v67, v87, v87
	v_add_f32_e32 v69, v66, v67
	v_cvt_pk_bf16_f32 v75, v80, v81
	ds_bpermute_b32 v80, v195, v69
	v_lshl_add_u64 v[66:67], s[68:69], 0, v[178:179]
	v_cvt_pk_bf16_f32 v74, v78, v79
	v_lshl_add_u64 v[78:79], v[170:171], 1, v[66:67]
	v_cvt_pk_bf16_f32 v76, v84, v85
	s_waitcnt lgkmcnt(0)
	v_add_f32_e32 v66, v69, v80
	ds_bpermute_b32 v67, v114, v66
	v_cvt_pk_bf16_f32 v77, v82, v83
	v_cvt_pk_bf16_f32 v68, v70, v71
	v_cvt_pk_bf16_f32 v69, v72, v73
	v_cvt_pk_bf16_f32 v70, v88, v89
	v_cvt_pk_bf16_f32 v71, v86, v87
	global_store_dwordx4 v[78:79], v[74:77], off sc0 sc1
	global_store_dwordx4 v[78:79], v[68:71], off offset:256 sc0 sc1
	s_and_saveexec_b64 s[20:21], s[2:3]
	s_cbranch_execz .LBB0_595
	s_waitcnt lgkmcnt(0)
	v_add_f32_e32 v68, v66, v67
	v_lshl_add_u64 v[66:67], v[176:177], 2, s[6:7]
	global_atomic_add_f32 v[66:67], v68, off
.LBB0_595:
	s_or_b64 exec, exec, s[20:21]
	v_add_u32_e32 v102, 0x80, v174
	v_ashrrev_i32_e32 v103, 31, v102
	v_lshlrev_b64 v[112:113], 11, v[102:103]
	s_waitcnt lgkmcnt(0)
	v_lshl_add_u64 v[66:67], v[172:173], 0, v[112:113]
	global_load_dwordx4 v[104:107], v[66:67], off
	global_load_dwordx4 v[108:111], v[66:67], off offset:256
	v_add_u32_e32 v98, 0x90, v174
	v_add_u32_e32 v94, 0xa0, v174
	v_add_u32_e32 v90, 0xb0, v174
	v_ashrrev_i32_e32 v99, 31, v98
	v_ashrrev_i32_e32 v95, 31, v94
	v_ashrrev_i32_e32 v91, 31, v90
	v_lshlrev_b64 v[100:101], 11, v[98:99]
	v_lshlrev_b64 v[96:97], 11, v[94:95]
	v_lshlrev_b64 v[92:93], 11, v[90:91]
	v_lshl_add_u64 v[66:67], v[172:173], 0, v[100:101]
	v_lshl_add_u64 v[68:69], v[172:173], 0, v[96:97]
	v_lshl_add_u64 v[116:117], v[172:173], 0, v[92:93]
	global_load_dwordx4 v[86:89], v[66:67], off
	global_load_dwordx4 v[82:85], v[66:67], off offset:256
	global_load_dwordx4 v[78:81], v[68:69], off
	global_load_dwordx4 v[74:77], v[68:69], off offset:256
	global_load_dwordx4 v[70:73], v[116:117], off
	s_nop 0
	global_load_dwordx4 v[66:69], v[116:117], off offset:256
	s_waitcnt vmcnt(7)
	v_lshlrev_b32_e32 v116, 16, v104
	v_and_b32_e32 v117, 0xffff0000, v104
	s_waitcnt vmcnt(6)
	v_lshlrev_b32_e32 v120, 16, v108
	v_and_b32_e32 v121, 0xffff0000, v108
	v_lshlrev_b32_e32 v118, 16, v106
	v_and_b32_e32 v119, 0xffff0000, v106
	v_lshlrev_b32_e32 v106, 16, v107
	v_and_b32_e32 v107, 0xffff0000, v107
	v_lshlrev_b32_e32 v108, 16, v109
	v_and_b32_e32 v109, 0xffff0000, v109
	v_lshlrev_b32_e32 v122, 16, v110
	v_and_b32_e32 v123, 0xffff0000, v110
	v_pk_add_f32 v[62:63], v[62:63], v[116:117]
	v_pk_add_f32 v[54:55], v[54:55], v[120:121]
	v_lshlrev_b32_e32 v104, 16, v105
	v_and_b32_e32 v105, 0xffff0000, v105
	v_pk_add_f32 v[60:61], v[60:61], v[106:107]
	v_pk_add_f32 v[56:57], v[56:57], v[108:109]
	v_pk_add_f32 v[106:107], v[50:51], v[122:123]
	v_cvt_pk_bf16_f32 v50, v62, v63
	v_mul_f32_e32 v63, v63, v63
	v_mul_f32_e32 v108, v55, v55
	v_pk_add_f32 v[64:65], v[64:65], v[104:105]
	v_fmac_f32_e32 v63, v62, v62
	v_fmac_f32_e32 v108, v54, v54
	v_fmac_f32_e32 v63, v64, v64
	v_fmac_f32_e32 v108, v56, v56
	v_pk_add_f32 v[58:59], v[58:59], v[118:119]
	v_fmac_f32_e32 v63, v65, v65
	v_fmac_f32_e32 v108, v57, v57
	v_lshlrev_b32_e32 v110, 16, v111
	v_and_b32_e32 v111, 0xffff0000, v111
	v_fmac_f32_e32 v63, v58, v58
	v_fmac_f32_e32 v108, v106, v106
	v_pk_add_f32 v[104:105], v[52:53], v[110:111]
	v_fmac_f32_e32 v63, v59, v59
	v_fmac_f32_e32 v108, v107, v107
	v_fmac_f32_e32 v63, v60, v60
	v_fmac_f32_e32 v108, v104, v104
	v_fmac_f32_e32 v63, v61, v61
	v_fmac_f32_e32 v108, v105, v105
	v_cvt_pk_bf16_f32 v53, v60, v61
	v_add_f32_e32 v60, v63, v108
	ds_bpermute_b32 v61, v195, v60
	v_cvt_pk_bf16_f32 v52, v58, v59
	v_lshl_add_u64 v[58:59], s[68:69], 0, v[112:113]
	v_cvt_pk_bf16_f32 v51, v64, v65
	v_lshl_add_u64 v[58:59], v[170:171], 1, v[58:59]
	global_store_dwordx4 v[58:59], v[50:53], off sc0 sc1
	s_waitcnt lgkmcnt(0)
	s_nop 0
	v_add_f32_e32 v50, v60, v61
	ds_bpermute_b32 v51, v114, v50
	v_cvt_pk_bf16_f32 v52, v54, v55
	v_cvt_pk_bf16_f32 v53, v56, v57
	v_cvt_pk_bf16_f32 v54, v106, v107
	v_cvt_pk_bf16_f32 v55, v104, v105
	global_store_dwordx4 v[58:59], v[52:55], off offset:256 sc0 sc1
	s_and_saveexec_b64 s[20:21], s[2:3]
	s_cbranch_execz .LBB0_597
	s_waitcnt lgkmcnt(0)
	v_add_f32_e32 v52, v50, v51
	v_lshl_add_u64 v[50:51], v[102:103], 2, s[6:7]
	global_atomic_add_f32 v[50:51], v52, off
.LBB0_597:
	s_or_b64 exec, exec, s[20:21]
	s_waitcnt vmcnt(7)
	v_lshlrev_b32_e32 v52, 16, v87
	v_and_b32_e32 v53, 0xffff0000, v87
	v_lshlrev_b32_e32 v54, 16, v88
	v_and_b32_e32 v55, 0xffff0000, v88
	v_lshlrev_b32_e32 v50, 16, v86
	s_waitcnt lgkmcnt(0)
	v_and_b32_e32 v51, 0xffff0000, v86
	v_lshlrev_b32_e32 v56, 16, v89
	v_and_b32_e32 v57, 0xffff0000, v89
	v_pk_add_f32 v[48:49], v[48:49], v[52:53]
	v_pk_add_f32 v[52:53], v[42:43], v[54:55]
	s_waitcnt vmcnt(6)
	v_lshlrev_b32_e32 v54, 16, v82
	v_and_b32_e32 v55, 0xffff0000, v82
	v_pk_add_f32 v[46:47], v[46:47], v[50:51]
	v_pk_add_f32 v[50:51], v[44:45], v[56:57]
	v_lshlrev_b32_e32 v56, 16, v83
	v_and_b32_e32 v57, 0xffff0000, v83
	v_lshlrev_b32_e32 v58, 16, v84
	v_and_b32_e32 v59, 0xffff0000, v84
	v_pk_add_f32 v[38:39], v[38:39], v[54:55]
	v_pk_add_f32 v[40:41], v[40:41], v[56:57]
	v_pk_add_f32 v[56:57], v[34:35], v[58:59]
	v_mul_f32_e32 v34, v47, v47
	v_mul_f32_e32 v35, v39, v39
	v_fmac_f32_e32 v34, v46, v46
	v_fmac_f32_e32 v35, v38, v38
	v_fmac_f32_e32 v34, v48, v48
	v_fmac_f32_e32 v35, v40, v40
	v_fmac_f32_e32 v34, v49, v49
	v_fmac_f32_e32 v35, v41, v41
	v_lshlrev_b32_e32 v60, 16, v85
	v_and_b32_e32 v61, 0xffff0000, v85
	v_fmac_f32_e32 v34, v52, v52
	v_fmac_f32_e32 v35, v56, v56
	v_pk_add_f32 v[54:55], v[36:37], v[60:61]
	v_fmac_f32_e32 v34, v53, v53
	v_fmac_f32_e32 v35, v57, v57
	v_fmac_f32_e32 v34, v50, v50
	v_fmac_f32_e32 v35, v54, v54
	v_fmac_f32_e32 v34, v51, v51
	v_fmac_f32_e32 v35, v55, v55
	v_add_f32_e32 v37, v34, v35
	v_cvt_pk_bf16_f32 v43, v48, v49
	ds_bpermute_b32 v48, v195, v37
	v_lshl_add_u64 v[34:35], s[68:69], 0, v[100:101]
	v_cvt_pk_bf16_f32 v42, v46, v47
	v_lshl_add_u64 v[46:47], v[170:171], 1, v[34:35]
	v_cvt_pk_bf16_f32 v44, v52, v53
	s_waitcnt lgkmcnt(0)
	v_add_f32_e32 v34, v37, v48
	ds_bpermute_b32 v35, v114, v34
	v_cvt_pk_bf16_f32 v45, v50, v51
	v_cvt_pk_bf16_f32 v36, v38, v39
	v_cvt_pk_bf16_f32 v37, v40, v41
	v_cvt_pk_bf16_f32 v38, v56, v57
	v_cvt_pk_bf16_f32 v39, v54, v55
	global_store_dwordx4 v[46:47], v[42:45], off sc0 sc1
	global_store_dwordx4 v[46:47], v[36:39], off offset:256 sc0 sc1
	s_and_saveexec_b64 s[20:21], s[2:3]
	s_cbranch_execz .LBB0_599
	s_waitcnt lgkmcnt(0)
	v_add_f32_e32 v36, v34, v35
	v_lshl_add_u64 v[34:35], v[98:99], 2, s[6:7]
	global_atomic_add_f32 v[34:35], v36, off
.LBB0_599:
	s_or_b64 exec, exec, s[20:21]
	s_waitcnt vmcnt(7)
	v_lshlrev_b32_e32 v36, 16, v79
	v_and_b32_e32 v37, 0xffff0000, v79
	v_lshlrev_b32_e32 v38, 16, v80
	v_and_b32_e32 v39, 0xffff0000, v80
	v_lshlrev_b32_e32 v34, 16, v78
	s_waitcnt lgkmcnt(0)
	v_and_b32_e32 v35, 0xffff0000, v78
	v_lshlrev_b32_e32 v40, 16, v81
	v_and_b32_e32 v41, 0xffff0000, v81
	v_pk_add_f32 v[32:33], v[32:33], v[36:37]
	v_pk_add_f32 v[36:37], v[26:27], v[38:39]
	s_waitcnt vmcnt(6)
	v_lshlrev_b32_e32 v38, 16, v74
	v_and_b32_e32 v39, 0xffff0000, v74
	v_pk_add_f32 v[30:31], v[30:31], v[34:35]
	v_pk_add_f32 v[34:35], v[28:29], v[40:41]
	v_lshlrev_b32_e32 v40, 16, v75
	v_and_b32_e32 v41, 0xffff0000, v75
	v_lshlrev_b32_e32 v42, 16, v76
	v_and_b32_e32 v43, 0xffff0000, v76
	v_pk_add_f32 v[22:23], v[22:23], v[38:39]
	v_pk_add_f32 v[24:25], v[24:25], v[40:41]
	v_pk_add_f32 v[40:41], v[18:19], v[42:43]
	v_mul_f32_e32 v18, v31, v31
	v_mul_f32_e32 v19, v23, v23
	v_fmac_f32_e32 v18, v30, v30
	v_fmac_f32_e32 v19, v22, v22
	v_fmac_f32_e32 v18, v32, v32
	v_fmac_f32_e32 v19, v24, v24
	v_fmac_f32_e32 v18, v33, v33
	v_fmac_f32_e32 v19, v25, v25
	v_lshlrev_b32_e32 v44, 16, v77
	v_and_b32_e32 v45, 0xffff0000, v77
	v_fmac_f32_e32 v18, v36, v36
	v_fmac_f32_e32 v19, v40, v40
	v_pk_add_f32 v[38:39], v[20:21], v[44:45]
	v_fmac_f32_e32 v18, v37, v37
	v_fmac_f32_e32 v19, v41, v41
	v_fmac_f32_e32 v18, v34, v34
	v_fmac_f32_e32 v19, v38, v38
	v_fmac_f32_e32 v18, v35, v35
	v_fmac_f32_e32 v19, v39, v39
	v_add_f32_e32 v21, v18, v19
	v_cvt_pk_bf16_f32 v27, v32, v33
	ds_bpermute_b32 v32, v195, v21
	v_lshl_add_u64 v[18:19], s[68:69], 0, v[96:97]
	v_cvt_pk_bf16_f32 v26, v30, v31
	v_lshl_add_u64 v[30:31], v[170:171], 1, v[18:19]
	v_cvt_pk_bf16_f32 v28, v36, v37
	s_waitcnt lgkmcnt(0)
	v_add_f32_e32 v18, v21, v32
	ds_bpermute_b32 v19, v114, v18
	v_cvt_pk_bf16_f32 v29, v34, v35
	v_cvt_pk_bf16_f32 v20, v22, v23
	v_cvt_pk_bf16_f32 v21, v24, v25
	v_cvt_pk_bf16_f32 v22, v40, v41
	v_cvt_pk_bf16_f32 v23, v38, v39
	global_store_dwordx4 v[30:31], v[26:29], off sc0 sc1
	global_store_dwordx4 v[30:31], v[20:23], off offset:256 sc0 sc1
	s_and_saveexec_b64 s[20:21], s[2:3]
	s_cbranch_execz .LBB0_601
	s_waitcnt lgkmcnt(0)
	v_add_f32_e32 v20, v18, v19
	v_lshl_add_u64 v[18:19], v[94:95], 2, s[6:7]
	global_atomic_add_f32 v[18:19], v20, off
.LBB0_601:
	s_or_b64 exec, exec, s[20:21]
	s_waitcnt vmcnt(7)
	v_lshlrev_b32_e32 v20, 16, v71
	v_and_b32_e32 v21, 0xffff0000, v71
	v_lshlrev_b32_e32 v22, 16, v72
	v_and_b32_e32 v23, 0xffff0000, v72
	v_lshlrev_b32_e32 v18, 16, v70
	s_waitcnt lgkmcnt(0)
	v_and_b32_e32 v19, 0xffff0000, v70
	v_lshlrev_b32_e32 v24, 16, v73
	v_and_b32_e32 v25, 0xffff0000, v73
	v_pk_add_f32 v[16:17], v[16:17], v[20:21]
	v_pk_add_f32 v[20:21], v[10:11], v[22:23]
	s_waitcnt vmcnt(6)
	v_lshlrev_b32_e32 v22, 16, v66
	v_and_b32_e32 v23, 0xffff0000, v66
	v_pk_add_f32 v[14:15], v[14:15], v[18:19]
	v_pk_add_f32 v[18:19], v[12:13], v[24:25]
	v_lshlrev_b32_e32 v24, 16, v67
	v_and_b32_e32 v25, 0xffff0000, v67
	v_lshlrev_b32_e32 v26, 16, v68
	v_and_b32_e32 v27, 0xffff0000, v68
	v_pk_add_f32 v[6:7], v[6:7], v[22:23]
	v_pk_add_f32 v[8:9], v[8:9], v[24:25]
	v_pk_add_f32 v[24:25], v[2:3], v[26:27]
	v_mul_f32_e32 v2, v15, v15
	v_mul_f32_e32 v3, v7, v7
	v_fmac_f32_e32 v2, v14, v14
	v_fmac_f32_e32 v3, v6, v6
	v_fmac_f32_e32 v2, v16, v16
	v_fmac_f32_e32 v3, v8, v8
	v_fmac_f32_e32 v2, v17, v17
	v_fmac_f32_e32 v3, v9, v9
	v_lshlrev_b32_e32 v28, 16, v69
	v_and_b32_e32 v29, 0xffff0000, v69
	v_fmac_f32_e32 v2, v20, v20
	v_fmac_f32_e32 v3, v24, v24
	v_pk_add_f32 v[22:23], v[4:5], v[28:29]
	v_fmac_f32_e32 v2, v21, v21
	v_fmac_f32_e32 v3, v25, v25
	v_fmac_f32_e32 v2, v18, v18
	v_fmac_f32_e32 v3, v22, v22
	v_fmac_f32_e32 v2, v19, v19
	v_fmac_f32_e32 v3, v23, v23
	v_add_f32_e32 v5, v2, v3
	v_cvt_pk_bf16_f32 v11, v16, v17
	ds_bpermute_b32 v16, v195, v5
	v_lshl_add_u64 v[2:3], s[68:69], 0, v[92:93]
	v_cvt_pk_bf16_f32 v10, v14, v15
	v_lshl_add_u64 v[14:15], v[170:171], 1, v[2:3]
	v_cvt_pk_bf16_f32 v12, v20, v21
	s_waitcnt lgkmcnt(0)
	v_add_f32_e32 v2, v5, v16
	ds_bpermute_b32 v3, v114, v2
	v_cvt_pk_bf16_f32 v13, v18, v19
	v_cvt_pk_bf16_f32 v4, v6, v7
	v_cvt_pk_bf16_f32 v5, v8, v9
	v_cvt_pk_bf16_f32 v6, v24, v25
	v_cvt_pk_bf16_f32 v7, v22, v23
	global_store_dwordx4 v[14:15], v[10:13], off sc0 sc1
	global_store_dwordx4 v[14:15], v[4:7], off offset:256 sc0 sc1
	s_and_saveexec_b64 s[20:21], s[2:3]
	s_cbranch_execz .LBB0_578
	s_waitcnt lgkmcnt(0)
	v_add_f32_e32 v4, v2, v3
	v_lshl_add_u64 v[2:3], v[90:91], 2, s[6:7]
	global_atomic_add_f32 v[2:3], v4, off
	s_branch .LBB0_578

.Lgemm_epi4:
	s_mov_b32 s56, 0xbfb8aa3b
	v_lshl_add_u32 v146, s43, 10, v154
	ds_read2_b32 v[234:235], v146 offset1:16
	ds_read2_b32 v[236:237], v146 offset0:32 offset1:48
	ds_read2_b32 v[238:239], v146 offset0:128 offset1:144
	ds_read2_b32 v[240:241], v146 offset0:160 offset1:176
	v_lshl_or_b32 v162, s44, 7, v155
	v_ashrrev_i32_e32 v163, 31, v162
	v_lshl_add_u32 v159, s18, 8, v152
	v_lshlrev_b64 v[242:243], 1, v[162:163]
	v_lshl_add_u64 v[242:243], s[4:5], 0, v[242:243]
	s_and_b64 vcc, exec, s[2:3]
	s_mov_b32 s44, s8
	s_mov_b32 s18, s12
	s_mov_b64 s[22:23], s[16:17]
	s_mov_b64 s[20:21], s[14:15]
	s_mov_b32 s43, s42
	s_waitcnt lgkmcnt(0)
	v_mad_i64_i32 v[244:245], s[0:1], v159, s41, v[242:243]
	v_pk_mul_f32 v[126:127], v[126:127], v[234:235] op_sel_hi:[1,0]
	v_pk_mul_f32 v[128:129], v[128:129], v[234:235] op_sel_hi:[1,0]
	v_pk_mul_f32 v[122:123], v[122:123], v[234:235] op_sel_hi:[1,0]
	v_pk_mul_f32 v[124:125], v[124:125], v[234:235] op_sel_hi:[1,0]
	v_pk_mul_f32 v[118:119], v[118:119], v[234:235] op_sel_hi:[1,0]
	v_pk_mul_f32 v[120:121], v[120:121], v[234:235] op_sel_hi:[1,0]
	v_pk_mul_f32 v[114:115], v[114:115], v[234:235] op_sel_hi:[1,0]
	v_pk_mul_f32 v[116:117], v[116:117], v[234:235] op_sel_hi:[1,0]
	v_pk_mul_f32 v[226:227], v[126:127], s[56:57] op_sel_hi:[1,0]
	v_pk_mul_f32 v[228:229], v[128:129], s[56:57] op_sel_hi:[1,0]
	v_pk_mul_f32 v[230:231], v[122:123], s[56:57] op_sel_hi:[1,0]
	v_pk_mul_f32 v[232:233], v[124:125], s[56:57] op_sel_hi:[1,0]
	v_exp_f32_e32 v226, v226
	v_exp_f32_e32 v227, v227
	v_exp_f32_e32 v228, v228
	v_exp_f32_e32 v229, v229
	v_exp_f32_e32 v230, v230
	v_exp_f32_e32 v231, v231
	v_exp_f32_e32 v232, v232
	v_exp_f32_e32 v233, v233
	v_pk_add_f32 v[226:227], v[226:227], 1.0 op_sel_hi:[1,0]
	v_pk_add_f32 v[228:229], v[228:229], 1.0 op_sel_hi:[1,0]
	v_pk_add_f32 v[230:231], v[230:231], 1.0 op_sel_hi:[1,0]
	v_pk_add_f32 v[232:233], v[232:233], 1.0 op_sel_hi:[1,0]
	v_rcp_f32_e32 v226, v226
	v_rcp_f32_e32 v227, v227
	v_rcp_f32_e32 v228, v228
	v_rcp_f32_e32 v229, v229
	v_rcp_f32_e32 v230, v230
	v_rcp_f32_e32 v231, v231
	v_rcp_f32_e32 v232, v232
	v_rcp_f32_e32 v233, v233
	v_pk_mul_f32 v[126:127], v[126:127], v[226:227]
	v_pk_mul_f32 v[128:129], v[128:129], v[228:229]
	v_pk_mul_f32 v[122:123], v[122:123], v[230:231]
	v_pk_mul_f32 v[124:125], v[124:125], v[232:233]
	v_pk_mul_f32 v[118:119], v[126:127], v[118:119]
	v_pk_mul_f32 v[120:121], v[128:129], v[120:121]
	v_pk_mul_f32 v[114:115], v[122:123], v[114:115]
	v_pk_mul_f32 v[116:117], v[124:125], v[116:117]
	v_cvt_pk_bf16_f32 v118, v118, v119
	v_cvt_pk_bf16_f32 v119, v120, v121
	v_cvt_pk_bf16_f32 v120, v114, v115
	v_cvt_pk_bf16_f32 v121, v116, v117
	global_store_dwordx4 v[244:245], v[118:121], off sc0 sc1
	v_add_u32_e32 v160, 16, v159
	v_mad_i64_i32 v[164:165], s[0:1], v160, s41, v[242:243]
	v_pk_mul_f32 v[110:111], v[110:111], v[234:235] op_sel:[0,1] op_sel_hi:[1,1]
	v_pk_mul_f32 v[112:113], v[112:113], v[234:235] op_sel:[0,1] op_sel_hi:[1,1]
	v_pk_mul_f32 v[106:107], v[106:107], v[234:235] op_sel:[0,1] op_sel_hi:[1,1]
	v_pk_mul_f32 v[108:109], v[108:109], v[234:235] op_sel:[0,1] op_sel_hi:[1,1]
	v_pk_mul_f32 v[102:103], v[102:103], v[234:235] op_sel:[0,1] op_sel_hi:[1,1]
	v_pk_mul_f32 v[104:105], v[104:105], v[234:235] op_sel:[0,1] op_sel_hi:[1,1]
	v_pk_mul_f32 v[98:99], v[98:99], v[234:235] op_sel:[0,1] op_sel_hi:[1,1]
	v_pk_mul_f32 v[100:101], v[100:101], v[234:235] op_sel:[0,1] op_sel_hi:[1,1]
	v_pk_mul_f32 v[226:227], v[110:111], s[56:57] op_sel_hi:[1,0]
	v_pk_mul_f32 v[228:229], v[112:113], s[56:57] op_sel_hi:[1,0]
	v_pk_mul_f32 v[230:231], v[106:107], s[56:57] op_sel_hi:[1,0]
	v_pk_mul_f32 v[232:233], v[108:109], s[56:57] op_sel_hi:[1,0]
	v_exp_f32_e32 v226, v226
	v_exp_f32_e32 v227, v227
	v_exp_f32_e32 v228, v228
	v_exp_f32_e32 v229, v229
	v_exp_f32_e32 v230, v230
	v_exp_f32_e32 v231, v231
	v_exp_f32_e32 v232, v232
	v_exp_f32_e32 v233, v233
	v_pk_add_f32 v[226:227], v[226:227], 1.0 op_sel_hi:[1,0]
	v_pk_add_f32 v[228:229], v[228:229], 1.0 op_sel_hi:[1,0]
	v_pk_add_f32 v[230:231], v[230:231], 1.0 op_sel_hi:[1,0]
	v_pk_add_f32 v[232:233], v[232:233], 1.0 op_sel_hi:[1,0]
	v_rcp_f32_e32 v226, v226
	v_rcp_f32_e32 v227, v227
	v_rcp_f32_e32 v228, v228
	v_rcp_f32_e32 v229, v229
	v_rcp_f32_e32 v230, v230
	v_rcp_f32_e32 v231, v231
	v_rcp_f32_e32 v232, v232
	v_rcp_f32_e32 v233, v233
	v_pk_mul_f32 v[110:111], v[110:111], v[226:227]
	v_pk_mul_f32 v[112:113], v[112:113], v[228:229]
	v_pk_mul_f32 v[106:107], v[106:107], v[230:231]
	v_pk_mul_f32 v[108:109], v[108:109], v[232:233]
	v_pk_mul_f32 v[102:103], v[110:111], v[102:103]
	v_pk_mul_f32 v[104:105], v[112:113], v[104:105]
	v_pk_mul_f32 v[98:99], v[106:107], v[98:99]
	v_pk_mul_f32 v[100:101], v[108:109], v[100:101]
	v_cvt_pk_bf16_f32 v102, v102, v103
	v_cvt_pk_bf16_f32 v103, v104, v105
	v_cvt_pk_bf16_f32 v104, v98, v99
	v_cvt_pk_bf16_f32 v105, v100, v101
	global_store_dwordx4 v[164:165], v[102:105], off sc0 sc1
	v_add_u32_e32 v160, 32, v159
	v_mad_i64_i32 v[244:245], s[0:1], v160, s41, v[242:243]
	v_pk_mul_f32 v[94:95], v[94:95], v[236:237] op_sel_hi:[1,0]
	v_pk_mul_f32 v[96:97], v[96:97], v[236:237] op_sel_hi:[1,0]
	v_pk_mul_f32 v[90:91], v[90:91], v[236:237] op_sel_hi:[1,0]
	v_pk_mul_f32 v[92:93], v[92:93], v[236:237] op_sel_hi:[1,0]
	v_pk_mul_f32 v[86:87], v[86:87], v[236:237] op_sel_hi:[1,0]
	v_pk_mul_f32 v[88:89], v[88:89], v[236:237] op_sel_hi:[1,0]
	v_pk_mul_f32 v[82:83], v[82:83], v[236:237] op_sel_hi:[1,0]
	v_pk_mul_f32 v[84:85], v[84:85], v[236:237] op_sel_hi:[1,0]
	v_pk_mul_f32 v[226:227], v[94:95], s[56:57] op_sel_hi:[1,0]
	v_pk_mul_f32 v[228:229], v[96:97], s[56:57] op_sel_hi:[1,0]
	v_pk_mul_f32 v[230:231], v[90:91], s[56:57] op_sel_hi:[1,0]
	v_pk_mul_f32 v[232:233], v[92:93], s[56:57] op_sel_hi:[1,0]
	v_exp_f32_e32 v226, v226
	v_exp_f32_e32 v227, v227
	v_exp_f32_e32 v228, v228
	v_exp_f32_e32 v229, v229
	v_exp_f32_e32 v230, v230
	v_exp_f32_e32 v231, v231
	v_exp_f32_e32 v232, v232
	v_exp_f32_e32 v233, v233
	v_pk_add_f32 v[226:227], v[226:227], 1.0 op_sel_hi:[1,0]
	v_pk_add_f32 v[228:229], v[228:229], 1.0 op_sel_hi:[1,0]
	v_pk_add_f32 v[230:231], v[230:231], 1.0 op_sel_hi:[1,0]
	v_pk_add_f32 v[232:233], v[232:233], 1.0 op_sel_hi:[1,0]
	v_rcp_f32_e32 v226, v226
	v_rcp_f32_e32 v227, v227
	v_rcp_f32_e32 v228, v228
	v_rcp_f32_e32 v229, v229
	v_rcp_f32_e32 v230, v230
	v_rcp_f32_e32 v231, v231
	v_rcp_f32_e32 v232, v232
	v_rcp_f32_e32 v233, v233
	v_pk_mul_f32 v[94:95], v[94:95], v[226:227]
	v_pk_mul_f32 v[96:97], v[96:97], v[228:229]
	v_pk_mul_f32 v[90:91], v[90:91], v[230:231]
	v_pk_mul_f32 v[92:93], v[92:93], v[232:233]
	v_pk_mul_f32 v[86:87], v[94:95], v[86:87]
	v_pk_mul_f32 v[88:89], v[96:97], v[88:89]
	v_pk_mul_f32 v[82:83], v[90:91], v[82:83]
	v_pk_mul_f32 v[84:85], v[92:93], v[84:85]
	v_cvt_pk_bf16_f32 v86, v86, v87
	v_cvt_pk_bf16_f32 v87, v88, v89
	v_cvt_pk_bf16_f32 v88, v82, v83
	v_cvt_pk_bf16_f32 v89, v84, v85
	global_store_dwordx4 v[244:245], v[86:89], off sc0 sc1
	v_add_u32_e32 v160, 48, v159
	v_mad_i64_i32 v[164:165], s[0:1], v160, s41, v[242:243]
	v_pk_mul_f32 v[78:79], v[78:79], v[236:237] op_sel:[0,1] op_sel_hi:[1,1]
	v_pk_mul_f32 v[80:81], v[80:81], v[236:237] op_sel:[0,1] op_sel_hi:[1,1]
	v_pk_mul_f32 v[74:75], v[74:75], v[236:237] op_sel:[0,1] op_sel_hi:[1,1]
	v_pk_mul_f32 v[76:77], v[76:77], v[236:237] op_sel:[0,1] op_sel_hi:[1,1]
	v_pk_mul_f32 v[70:71], v[70:71], v[236:237] op_sel:[0,1] op_sel_hi:[1,1]
	v_pk_mul_f32 v[72:73], v[72:73], v[236:237] op_sel:[0,1] op_sel_hi:[1,1]
	v_pk_mul_f32 v[66:67], v[66:67], v[236:237] op_sel:[0,1] op_sel_hi:[1,1]
	v_pk_mul_f32 v[68:69], v[68:69], v[236:237] op_sel:[0,1] op_sel_hi:[1,1]
	v_pk_mul_f32 v[226:227], v[78:79], s[56:57] op_sel_hi:[1,0]
	v_pk_mul_f32 v[228:229], v[80:81], s[56:57] op_sel_hi:[1,0]
	v_pk_mul_f32 v[230:231], v[74:75], s[56:57] op_sel_hi:[1,0]
	v_pk_mul_f32 v[232:233], v[76:77], s[56:57] op_sel_hi:[1,0]
	v_exp_f32_e32 v226, v226
	v_exp_f32_e32 v227, v227
	v_exp_f32_e32 v228, v228
	v_exp_f32_e32 v229, v229
	v_exp_f32_e32 v230, v230
	v_exp_f32_e32 v231, v231
	v_exp_f32_e32 v232, v232
	v_exp_f32_e32 v233, v233
	v_pk_add_f32 v[226:227], v[226:227], 1.0 op_sel_hi:[1,0]
	v_pk_add_f32 v[228:229], v[228:229], 1.0 op_sel_hi:[1,0]
	v_pk_add_f32 v[230:231], v[230:231], 1.0 op_sel_hi:[1,0]
	v_pk_add_f32 v[232:233], v[232:233], 1.0 op_sel_hi:[1,0]
	v_rcp_f32_e32 v226, v226
	v_rcp_f32_e32 v227, v227
	v_rcp_f32_e32 v228, v228
	v_rcp_f32_e32 v229, v229
	v_rcp_f32_e32 v230, v230
	v_rcp_f32_e32 v231, v231
	v_rcp_f32_e32 v232, v232
	v_rcp_f32_e32 v233, v233
	v_pk_mul_f32 v[78:79], v[78:79], v[226:227]
	v_pk_mul_f32 v[80:81], v[80:81], v[228:229]
	v_pk_mul_f32 v[74:75], v[74:75], v[230:231]
	v_pk_mul_f32 v[76:77], v[76:77], v[232:233]
	v_pk_mul_f32 v[70:71], v[78:79], v[70:71]
	v_pk_mul_f32 v[72:73], v[80:81], v[72:73]
	v_pk_mul_f32 v[66:67], v[74:75], v[66:67]
	v_pk_mul_f32 v[68:69], v[76:77], v[68:69]
	v_cvt_pk_bf16_f32 v70, v70, v71
	v_cvt_pk_bf16_f32 v71, v72, v73
	v_cvt_pk_bf16_f32 v72, v66, v67
	v_cvt_pk_bf16_f32 v73, v68, v69
	global_store_dwordx4 v[164:165], v[70:73], off sc0 sc1
	v_add_u32_e32 v160, 128, v159
	v_mad_i64_i32 v[244:245], s[0:1], v160, s41, v[242:243]
	v_pk_mul_f32 v[62:63], v[62:63], v[238:239] op_sel_hi:[1,0]
	v_pk_mul_f32 v[64:65], v[64:65], v[238:239] op_sel_hi:[1,0]
	v_pk_mul_f32 v[58:59], v[58:59], v[238:239] op_sel_hi:[1,0]
	v_pk_mul_f32 v[60:61], v[60:61], v[238:239] op_sel_hi:[1,0]
	v_pk_mul_f32 v[54:55], v[54:55], v[238:239] op_sel_hi:[1,0]
	v_pk_mul_f32 v[56:57], v[56:57], v[238:239] op_sel_hi:[1,0]
	v_pk_mul_f32 v[50:51], v[50:51], v[238:239] op_sel_hi:[1,0]
	v_pk_mul_f32 v[52:53], v[52:53], v[238:239] op_sel_hi:[1,0]
	v_pk_mul_f32 v[226:227], v[62:63], s[56:57] op_sel_hi:[1,0]
	v_pk_mul_f32 v[228:229], v[64:65], s[56:57] op_sel_hi:[1,0]
	v_pk_mul_f32 v[230:231], v[58:59], s[56:57] op_sel_hi:[1,0]
	v_pk_mul_f32 v[232:233], v[60:61], s[56:57] op_sel_hi:[1,0]
	v_exp_f32_e32 v226, v226
	v_exp_f32_e32 v227, v227
	v_exp_f32_e32 v228, v228
	v_exp_f32_e32 v229, v229
	v_exp_f32_e32 v230, v230
	v_exp_f32_e32 v231, v231
	v_exp_f32_e32 v232, v232
	v_exp_f32_e32 v233, v233
	v_pk_add_f32 v[226:227], v[226:227], 1.0 op_sel_hi:[1,0]
	v_pk_add_f32 v[228:229], v[228:229], 1.0 op_sel_hi:[1,0]
	v_pk_add_f32 v[230:231], v[230:231], 1.0 op_sel_hi:[1,0]
	v_pk_add_f32 v[232:233], v[232:233], 1.0 op_sel_hi:[1,0]
	v_rcp_f32_e32 v226, v226
	v_rcp_f32_e32 v227, v227
	v_rcp_f32_e32 v228, v228
	v_rcp_f32_e32 v229, v229
	v_rcp_f32_e32 v230, v230
	v_rcp_f32_e32 v231, v231
	v_rcp_f32_e32 v232, v232
	v_rcp_f32_e32 v233, v233
	v_pk_mul_f32 v[62:63], v[62:63], v[226:227]
	v_pk_mul_f32 v[64:65], v[64:65], v[228:229]
	v_pk_mul_f32 v[58:59], v[58:59], v[230:231]
	v_pk_mul_f32 v[60:61], v[60:61], v[232:233]
	v_pk_mul_f32 v[54:55], v[62:63], v[54:55]
	v_pk_mul_f32 v[56:57], v[64:65], v[56:57]
	v_pk_mul_f32 v[50:51], v[58:59], v[50:51]
	v_pk_mul_f32 v[52:53], v[60:61], v[52:53]
	v_cvt_pk_bf16_f32 v54, v54, v55
	v_cvt_pk_bf16_f32 v55, v56, v57
	v_cvt_pk_bf16_f32 v56, v50, v51
	v_cvt_pk_bf16_f32 v57, v52, v53
	global_store_dwordx4 v[244:245], v[54:57], off sc0 sc1
	v_add_u32_e32 v160, 144, v159
	v_mad_i64_i32 v[164:165], s[0:1], v160, s41, v[242:243]
	v_pk_mul_f32 v[46:47], v[46:47], v[238:239] op_sel:[0,1] op_sel_hi:[1,1]
	v_pk_mul_f32 v[48:49], v[48:49], v[238:239] op_sel:[0,1] op_sel_hi:[1,1]
	v_pk_mul_f32 v[42:43], v[42:43], v[238:239] op_sel:[0,1] op_sel_hi:[1,1]
	v_pk_mul_f32 v[44:45], v[44:45], v[238:239] op_sel:[0,1] op_sel_hi:[1,1]
	v_pk_mul_f32 v[38:39], v[38:39], v[238:239] op_sel:[0,1] op_sel_hi:[1,1]
	v_pk_mul_f32 v[40:41], v[40:41], v[238:239] op_sel:[0,1] op_sel_hi:[1,1]
	v_pk_mul_f32 v[34:35], v[34:35], v[238:239] op_sel:[0,1] op_sel_hi:[1,1]
	v_pk_mul_f32 v[36:37], v[36:37], v[238:239] op_sel:[0,1] op_sel_hi:[1,1]
	v_pk_mul_f32 v[226:227], v[46:47], s[56:57] op_sel_hi:[1,0]
	v_pk_mul_f32 v[228:229], v[48:49], s[56:57] op_sel_hi:[1,0]
	v_pk_mul_f32 v[230:231], v[42:43], s[56:57] op_sel_hi:[1,0]
	v_pk_mul_f32 v[232:233], v[44:45], s[56:57] op_sel_hi:[1,0]
	v_exp_f32_e32 v226, v226
	v_exp_f32_e32 v227, v227
	v_exp_f32_e32 v228, v228
	v_exp_f32_e32 v229, v229
	v_exp_f32_e32 v230, v230
	v_exp_f32_e32 v231, v231
	v_exp_f32_e32 v232, v232
	v_exp_f32_e32 v233, v233
	v_pk_add_f32 v[226:227], v[226:227], 1.0 op_sel_hi:[1,0]
	v_pk_add_f32 v[228:229], v[228:229], 1.0 op_sel_hi:[1,0]
	v_pk_add_f32 v[230:231], v[230:231], 1.0 op_sel_hi:[1,0]
	v_pk_add_f32 v[232:233], v[232:233], 1.0 op_sel_hi:[1,0]
	v_rcp_f32_e32 v226, v226
	v_rcp_f32_e32 v227, v227
	v_rcp_f32_e32 v228, v228
	v_rcp_f32_e32 v229, v229
	v_rcp_f32_e32 v230, v230
	v_rcp_f32_e32 v231, v231
	v_rcp_f32_e32 v232, v232
	v_rcp_f32_e32 v233, v233
	v_pk_mul_f32 v[46:47], v[46:47], v[226:227]
	v_pk_mul_f32 v[48:49], v[48:49], v[228:229]
	v_pk_mul_f32 v[42:43], v[42:43], v[230:231]
	v_pk_mul_f32 v[44:45], v[44:45], v[232:233]
	v_pk_mul_f32 v[38:39], v[46:47], v[38:39]
	v_pk_mul_f32 v[40:41], v[48:49], v[40:41]
	v_pk_mul_f32 v[34:35], v[42:43], v[34:35]
	v_pk_mul_f32 v[36:37], v[44:45], v[36:37]
	v_cvt_pk_bf16_f32 v38, v38, v39
	v_cvt_pk_bf16_f32 v39, v40, v41
	v_cvt_pk_bf16_f32 v40, v34, v35
	v_cvt_pk_bf16_f32 v41, v36, v37
	global_store_dwordx4 v[164:165], v[38:41], off sc0 sc1
	v_add_u32_e32 v160, 160, v159
	v_mad_i64_i32 v[244:245], s[0:1], v160, s41, v[242:243]
	v_pk_mul_f32 v[30:31], v[30:31], v[240:241] op_sel_hi:[1,0]
	v_pk_mul_f32 v[32:33], v[32:33], v[240:241] op_sel_hi:[1,0]
	v_pk_mul_f32 v[26:27], v[26:27], v[240:241] op_sel_hi:[1,0]
	v_pk_mul_f32 v[28:29], v[28:29], v[240:241] op_sel_hi:[1,0]
	v_pk_mul_f32 v[22:23], v[22:23], v[240:241] op_sel_hi:[1,0]
	v_pk_mul_f32 v[24:25], v[24:25], v[240:241] op_sel_hi:[1,0]
	v_pk_mul_f32 v[18:19], v[18:19], v[240:241] op_sel_hi:[1,0]
	v_pk_mul_f32 v[20:21], v[20:21], v[240:241] op_sel_hi:[1,0]
	v_pk_mul_f32 v[226:227], v[30:31], s[56:57] op_sel_hi:[1,0]
	v_pk_mul_f32 v[228:229], v[32:33], s[56:57] op_sel_hi:[1,0]
	v_pk_mul_f32 v[230:231], v[26:27], s[56:57] op_sel_hi:[1,0]
	v_pk_mul_f32 v[232:233], v[28:29], s[56:57] op_sel_hi:[1,0]
	v_exp_f32_e32 v226, v226
	v_exp_f32_e32 v227, v227
	v_exp_f32_e32 v228, v228
	v_exp_f32_e32 v229, v229
	v_exp_f32_e32 v230, v230
	v_exp_f32_e32 v231, v231
	v_exp_f32_e32 v232, v232
	v_exp_f32_e32 v233, v233
	v_pk_add_f32 v[226:227], v[226:227], 1.0 op_sel_hi:[1,0]
	v_pk_add_f32 v[228:229], v[228:229], 1.0 op_sel_hi:[1,0]
	v_pk_add_f32 v[230:231], v[230:231], 1.0 op_sel_hi:[1,0]
	v_pk_add_f32 v[232:233], v[232:233], 1.0 op_sel_hi:[1,0]
	v_rcp_f32_e32 v226, v226
	v_rcp_f32_e32 v227, v227
	v_rcp_f32_e32 v228, v228
	v_rcp_f32_e32 v229, v229
	v_rcp_f32_e32 v230, v230
	v_rcp_f32_e32 v231, v231
	v_rcp_f32_e32 v232, v232
	v_rcp_f32_e32 v233, v233
	v_pk_mul_f32 v[30:31], v[30:31], v[226:227]
	v_pk_mul_f32 v[32:33], v[32:33], v[228:229]
	v_pk_mul_f32 v[26:27], v[26:27], v[230:231]
	v_pk_mul_f32 v[28:29], v[28:29], v[232:233]
	v_pk_mul_f32 v[22:23], v[30:31], v[22:23]
	v_pk_mul_f32 v[24:25], v[32:33], v[24:25]
	v_pk_mul_f32 v[18:19], v[26:27], v[18:19]
	v_pk_mul_f32 v[20:21], v[28:29], v[20:21]
	v_cvt_pk_bf16_f32 v22, v22, v23
	v_cvt_pk_bf16_f32 v23, v24, v25
	v_cvt_pk_bf16_f32 v24, v18, v19
	v_cvt_pk_bf16_f32 v25, v20, v21
	global_store_dwordx4 v[244:245], v[22:25], off sc0 sc1
	v_add_u32_e32 v160, 176, v159
	v_mad_i64_i32 v[164:165], s[0:1], v160, s41, v[242:243]
	v_pk_mul_f32 v[14:15], v[14:15], v[240:241] op_sel:[0,1] op_sel_hi:[1,1]
	v_pk_mul_f32 v[16:17], v[16:17], v[240:241] op_sel:[0,1] op_sel_hi:[1,1]
	v_pk_mul_f32 v[10:11], v[10:11], v[240:241] op_sel:[0,1] op_sel_hi:[1,1]
	v_pk_mul_f32 v[12:13], v[12:13], v[240:241] op_sel:[0,1] op_sel_hi:[1,1]
	v_pk_mul_f32 v[6:7], v[6:7], v[240:241] op_sel:[0,1] op_sel_hi:[1,1]
	v_pk_mul_f32 v[8:9], v[8:9], v[240:241] op_sel:[0,1] op_sel_hi:[1,1]
	v_pk_mul_f32 v[2:3], v[2:3], v[240:241] op_sel:[0,1] op_sel_hi:[1,1]
	v_pk_mul_f32 v[4:5], v[4:5], v[240:241] op_sel:[0,1] op_sel_hi:[1,1]
	v_pk_mul_f32 v[226:227], v[14:15], s[56:57] op_sel_hi:[1,0]
	v_pk_mul_f32 v[228:229], v[16:17], s[56:57] op_sel_hi:[1,0]
	v_pk_mul_f32 v[230:231], v[10:11], s[56:57] op_sel_hi:[1,0]
	v_pk_mul_f32 v[232:233], v[12:13], s[56:57] op_sel_hi:[1,0]
	v_exp_f32_e32 v226, v226
	v_exp_f32_e32 v227, v227
	v_exp_f32_e32 v228, v228
	v_exp_f32_e32 v229, v229
	v_exp_f32_e32 v230, v230
	v_exp_f32_e32 v231, v231
	v_exp_f32_e32 v232, v232
	v_exp_f32_e32 v233, v233
	v_pk_add_f32 v[226:227], v[226:227], 1.0 op_sel_hi:[1,0]
	v_pk_add_f32 v[228:229], v[228:229], 1.0 op_sel_hi:[1,0]
	v_pk_add_f32 v[230:231], v[230:231], 1.0 op_sel_hi:[1,0]
	v_pk_add_f32 v[232:233], v[232:233], 1.0 op_sel_hi:[1,0]
	v_rcp_f32_e32 v226, v226
	v_rcp_f32_e32 v227, v227
	v_rcp_f32_e32 v228, v228
	v_rcp_f32_e32 v229, v229
	v_rcp_f32_e32 v230, v230
	v_rcp_f32_e32 v231, v231
	v_rcp_f32_e32 v232, v232
	v_rcp_f32_e32 v233, v233
	v_pk_mul_f32 v[14:15], v[14:15], v[226:227]
	v_pk_mul_f32 v[16:17], v[16:17], v[228:229]
	v_pk_mul_f32 v[10:11], v[10:11], v[230:231]
	v_pk_mul_f32 v[12:13], v[12:13], v[232:233]
	v_pk_mul_f32 v[6:7], v[14:15], v[6:7]
	v_pk_mul_f32 v[8:9], v[16:17], v[8:9]
	v_pk_mul_f32 v[2:3], v[10:11], v[2:3]
	v_pk_mul_f32 v[4:5], v[12:13], v[4:5]
	v_cvt_pk_bf16_f32 v6, v6, v7
	v_cvt_pk_bf16_f32 v7, v8, v9
	v_cvt_pk_bf16_f32 v8, v2, v3
	v_cvt_pk_bf16_f32 v9, v4, v5
	global_store_dwordx4 v[164:165], v[6:9], off sc0 sc1
	s_cbranch_vccz .LBB0_659
	s_waitcnt vmcnt(0)
	s_cmpk_gt_u32 s26, 0xff
	s_cbranch_scc1 .LBB0_666
	s_barrier

.Lgemm_epi5:
	v_lshl_add_u32 v148, s40, 8, v153
	v_lshl_or_b32 v144, s41, 8, v155
	v_ashrrev_i32_e32 v145, 31, v144
	v_ashrrev_i32_e32 v149, 31, v148
	v_lshl_add_u64 v[146:147], v[144:145], 1, s[14:15]
	v_lshlrev_b64 v[150:151], 11, v[148:149]
	v_or_b32_e32 v180, 16, v148
	v_lshl_add_u64 v[150:151], v[146:147], 0, v[150:151]
	v_ashrrev_i32_e32 v181, 31, v180
	global_load_dwordx4 v[160:163], v[150:151], off
	global_load_dwordx4 v[164:167], v[150:151], off offset:256
	v_lshlrev_b64 v[150:151], 11, v[180:181]
	v_or_b32_e32 v192, 32, v148
	v_lshl_add_u64 v[150:151], v[146:147], 0, v[150:151]
	v_ashrrev_i32_e32 v193, 31, v192
	global_load_dwordx4 v[168:171], v[150:151], off
	global_load_dwordx4 v[172:175], v[150:151], off offset:256
	v_lshlrev_b64 v[150:151], 11, v[192:193]
	v_lshl_add_u64 v[182:183], v[146:147], 0, v[150:151]
	global_load_dwordx4 v[176:179], v[182:183], off
	v_or_b32_e32 v150, 48, v148
	v_ashrrev_i32_e32 v151, 31, v150
	v_lshlrev_b64 v[188:189], 12, v[180:181]
	global_load_dwordx4 v[180:183], v[182:183], off offset:256
	v_lshlrev_b64 v[184:185], 12, v[148:149]
	v_lshlrev_b64 v[186:187], 11, v[150:151]
	v_lshlrev_b64 v[144:145], 2, v[144:145]
	v_lshl_add_u64 v[184:185], s[12:13], 0, v[184:185]
	v_lshl_add_u64 v[190:191], v[146:147], 0, v[186:187]
	v_lshl_add_u64 v[194:195], v[184:185], 0, v[144:145]
	v_lshl_add_u64 v[196:197], s[12:13], 0, v[188:189]
	global_load_dwordx4 v[184:187], v[190:191], off
	s_nop 0
	global_load_dwordx4 v[188:191], v[190:191], off offset:256
	v_lshl_add_u64 v[196:197], v[196:197], 0, v[144:145]
	s_and_b64 vcc, exec, s[0:1]
	s_mov_b32 s41, s38
	s_mov_b32 s40, s39
	s_mov_b64 s[16:17], s[4:5]
	s_mov_b64 s[8:9], s[2:3]
	s_waitcnt vmcnt(0)
	v_lshlrev_b32_e32 v198, 16, v160
	v_and_b32_e32 v199, 0xffff0000, v160
	v_lshlrev_b32_e32 v160, 16, v161
	v_and_b32_e32 v161, 0xffff0000, v161
	v_lshlrev_b32_e32 v200, 16, v162
	v_and_b32_e32 v201, 0xffff0000, v162
	v_lshlrev_b32_e32 v162, 16, v163
	v_and_b32_e32 v163, 0xffff0000, v163
	v_lshlrev_b32_e32 v202, 16, v164
	v_and_b32_e32 v203, 0xffff0000, v164
	v_lshlrev_b32_e32 v164, 16, v165
	v_and_b32_e32 v165, 0xffff0000, v165
	v_lshlrev_b32_e32 v204, 16, v166
	v_and_b32_e32 v205, 0xffff0000, v166
	v_lshlrev_b32_e32 v166, 16, v167
	v_and_b32_e32 v167, 0xffff0000, v167
	v_pk_fma_f32 v[126:127], v[126:127], 0.5, v[160:161] op_sel_hi:[1,0,1]
	v_pk_fma_f32 v[122:123], v[122:123], 0.5, v[162:163] op_sel_hi:[1,0,1]
	v_pk_fma_f32 v[118:119], v[118:119], 0.5, v[164:165] op_sel_hi:[1,0,1]
	v_pk_fma_f32 v[114:115], v[114:115], 0.5, v[166:167] op_sel_hi:[1,0,1]
	v_lshlrev_b32_e32 v160, 16, v168
	v_and_b32_e32 v161, 0xffff0000, v168
	v_lshlrev_b32_e32 v162, 16, v169
	v_and_b32_e32 v163, 0xffff0000, v169
	v_lshlrev_b32_e32 v164, 16, v170
	v_and_b32_e32 v165, 0xffff0000, v170
	v_lshlrev_b32_e32 v166, 16, v171
	v_and_b32_e32 v167, 0xffff0000, v171
	v_lshlrev_b32_e32 v168, 16, v172
	v_and_b32_e32 v169, 0xffff0000, v172
	v_lshlrev_b32_e32 v170, 16, v173
	v_and_b32_e32 v171, 0xffff0000, v173
	v_lshlrev_b32_e32 v172, 16, v174
	v_and_b32_e32 v173, 0xffff0000, v174
	v_pk_fma_f32 v[124:125], v[124:125], 0.5, v[198:199] op_sel_hi:[1,0,1]
	v_lshlrev_b32_e32 v174, 16, v175
	v_and_b32_e32 v175, 0xffff0000, v175
	v_pk_fma_f32 v[110:111], v[110:111], 0.5, v[162:163] op_sel_hi:[1,0,1]
	v_pk_fma_f32 v[108:109], v[108:109], 0.5, v[160:161] op_sel_hi:[1,0,1]
	v_pk_fma_f32 v[96:97], v[96:97], 0.5, v[172:173] op_sel_hi:[1,0,1]
	v_pk_fma_f32 v[120:121], v[120:121], 0.5, v[200:201] op_sel_hi:[1,0,1]
	v_pk_fma_f32 v[116:117], v[116:117], 0.5, v[202:203] op_sel_hi:[1,0,1]
	v_pk_fma_f32 v[112:113], v[112:113], 0.5, v[204:205] op_sel_hi:[1,0,1]
	global_store_dwordx4 v[194:195], v[124:127], off sc0 sc1
	global_store_dwordx4 v[194:195], v[120:123], off offset:16 sc0 sc1
	global_store_dwordx4 v[194:195], v[116:119], off offset:512 sc0 sc1
	global_store_dwordx4 v[194:195], v[112:115], off offset:528 sc0 sc1
	v_pk_fma_f32 v[106:107], v[106:107], 0.5, v[166:167] op_sel_hi:[1,0,1]
	v_pk_fma_f32 v[104:105], v[104:105], 0.5, v[164:165] op_sel_hi:[1,0,1]
	v_pk_fma_f32 v[102:103], v[102:103], 0.5, v[170:171] op_sel_hi:[1,0,1]
	v_pk_fma_f32 v[100:101], v[100:101], 0.5, v[168:169] op_sel_hi:[1,0,1]
	v_pk_fma_f32 v[98:99], v[98:99], 0.5, v[174:175] op_sel_hi:[1,0,1]
	global_store_dwordx4 v[196:197], v[108:111], off sc0 sc1
	global_store_dwordx4 v[196:197], v[104:107], off offset:16 sc0 sc1
	global_store_dwordx4 v[196:197], v[100:103], off offset:512 sc0 sc1
	global_store_dwordx4 v[196:197], v[96:99], off offset:528 sc0 sc1
	s_nop 0
	v_lshlrev_b32_e32 v100, 16, v178
	v_lshlrev_b32_e32 v96, 16, v176
	v_and_b32_e32 v97, 0xffff0000, v176
	v_pk_fma_f32 v[92:93], v[92:93], 0.5, v[96:97] op_sel_hi:[1,0,1]
	v_lshlrev_b64 v[96:97], 12, v[192:193]
	v_lshlrev_b32_e32 v98, 16, v177
	v_and_b32_e32 v99, 0xffff0000, v177
	v_and_b32_e32 v101, 0xffff0000, v178
	v_lshlrev_b32_e32 v102, 16, v179
	v_and_b32_e32 v103, 0xffff0000, v179
	v_lshl_add_u64 v[96:97], s[12:13], 0, v[96:97]
	v_pk_fma_f32 v[94:95], v[94:95], 0.5, v[98:99] op_sel_hi:[1,0,1]
	v_pk_fma_f32 v[90:91], v[90:91], 0.5, v[102:103] op_sel_hi:[1,0,1]
	v_pk_fma_f32 v[88:89], v[88:89], 0.5, v[100:101] op_sel_hi:[1,0,1]
	v_lshl_add_u64 v[96:97], v[96:97], 0, v[144:145]
	global_store_dwordx4 v[96:97], v[92:95], off sc0 sc1
	global_store_dwordx4 v[96:97], v[88:91], off offset:16 sc0 sc1
	v_add_u32_e32 v98, 0x90, v148
	v_lshlrev_b32_e32 v92, 16, v182
	v_lshlrev_b32_e32 v88, 16, v180
	v_and_b32_e32 v89, 0xffff0000, v180
	v_lshlrev_b32_e32 v90, 16, v181
	v_and_b32_e32 v91, 0xffff0000, v181
	v_and_b32_e32 v93, 0xffff0000, v182
	v_lshlrev_b32_e32 v94, 16, v183
	v_and_b32_e32 v95, 0xffff0000, v183
	v_pk_fma_f32 v[86:87], v[86:87], 0.5, v[90:91] op_sel_hi:[1,0,1]
	v_pk_fma_f32 v[84:85], v[84:85], 0.5, v[88:89] op_sel_hi:[1,0,1]
	v_pk_fma_f32 v[76:77], v[76:77], 0.5, v[92:93] op_sel_hi:[1,0,1]
	v_pk_fma_f32 v[78:79], v[78:79], 0.5, v[94:95] op_sel_hi:[1,0,1]
	global_store_dwordx4 v[96:97], v[84:87], off offset:512 sc0 sc1
	global_store_dwordx4 v[96:97], v[76:79], off offset:528 sc0 sc1
	v_add_u32_e32 v96, 0x80, v148
	v_lshlrev_b32_e32 v84, 16, v186
	v_lshlrev_b32_e32 v76, 16, v184
	v_and_b32_e32 v77, 0xffff0000, v184
	v_pk_fma_f32 v[76:77], v[80:81], 0.5, v[76:77] op_sel_hi:[1,0,1]
	v_lshlrev_b64 v[80:81], 12, v[150:151]
	v_lshlrev_b32_e32 v78, 16, v185
	v_and_b32_e32 v79, 0xffff0000, v185
	v_and_b32_e32 v85, 0xffff0000, v186
	v_lshlrev_b32_e32 v86, 16, v187
	v_and_b32_e32 v87, 0xffff0000, v187
	v_lshl_add_u64 v[80:81], s[12:13], 0, v[80:81]
	v_pk_fma_f32 v[78:79], v[82:83], 0.5, v[78:79] op_sel_hi:[1,0,1]
	v_pk_fma_f32 v[74:75], v[74:75], 0.5, v[86:87] op_sel_hi:[1,0,1]
	v_pk_fma_f32 v[72:73], v[72:73], 0.5, v[84:85] op_sel_hi:[1,0,1]
	v_lshl_add_u64 v[80:81], v[80:81], 0, v[144:145]
	global_store_dwordx4 v[80:81], v[76:79], off sc0 sc1
	global_store_dwordx4 v[80:81], v[72:75], off offset:16 sc0 sc1
	v_ashrrev_i32_e32 v97, 31, v96
	v_lshlrev_b32_e32 v76, 16, v190
	v_lshlrev_b32_e32 v72, 16, v188
	v_and_b32_e32 v73, 0xffff0000, v188
	v_lshlrev_b32_e32 v74, 16, v189
	v_and_b32_e32 v75, 0xffff0000, v189
	v_and_b32_e32 v77, 0xffff0000, v190
	v_lshlrev_b32_e32 v78, 16, v191
	v_and_b32_e32 v79, 0xffff0000, v191
	v_pk_fma_f32 v[70:71], v[70:71], 0.5, v[74:75] op_sel_hi:[1,0,1]
	v_pk_fma_f32 v[68:69], v[68:69], 0.5, v[72:73] op_sel_hi:[1,0,1]
	v_pk_fma_f32 v[64:65], v[64:65], 0.5, v[76:77] op_sel_hi:[1,0,1]
	v_pk_fma_f32 v[66:67], v[66:67], 0.5, v[78:79] op_sel_hi:[1,0,1]
	global_store_dwordx4 v[80:81], v[68:71], off offset:512 sc0 sc1
	global_store_dwordx4 v[80:81], v[64:67], off offset:528 sc0 sc1
	v_ashrrev_i32_e32 v99, 31, v98
	v_add_u32_e32 v100, 0xa0, v148
	v_lshlrev_b64 v[64:65], 11, v[96:97]
	v_lshl_add_u64 v[64:65], v[146:147], 0, v[64:65]
	global_load_dwordx4 v[68:71], v[64:65], off
	global_load_dwordx4 v[72:75], v[64:65], off offset:256
	v_lshlrev_b64 v[64:65], 11, v[98:99]
	v_lshl_add_u64 v[64:65], v[146:147], 0, v[64:65]
	global_load_dwordx4 v[76:79], v[64:65], off
	global_load_dwordx4 v[80:83], v[64:65], off offset:256
	v_ashrrev_i32_e32 v101, 31, v100
	v_lshlrev_b64 v[64:65], 11, v[100:101]
	v_lshl_add_u64 v[64:65], v[146:147], 0, v[64:65]
	global_load_dwordx4 v[84:87], v[64:65], off
	global_load_dwordx4 v[88:91], v[64:65], off offset:256
	v_add_u32_e32 v102, 0xb0, v148
	v_ashrrev_i32_e32 v103, 31, v102
	v_lshlrev_b64 v[64:65], 11, v[102:103]
	v_lshl_add_u64 v[64:65], v[146:147], 0, v[64:65]
	global_load_dwordx4 v[92:95], v[64:65], off
	s_nop 0
	global_load_dwordx4 v[64:67], v[64:65], off offset:256
	s_waitcnt vmcnt(0)
	v_lshlrev_b32_e32 v104, 16, v68
	v_and_b32_e32 v105, 0xffff0000, v68
	v_lshlrev_b32_e32 v68, 16, v69
	v_and_b32_e32 v69, 0xffff0000, v69
	v_pk_fma_f32 v[62:63], v[62:63], 0.5, v[68:69] op_sel_hi:[1,0,1]
	v_lshlrev_b64 v[68:69], 12, v[96:97]
	v_lshlrev_b32_e32 v106, 16, v70
	v_and_b32_e32 v107, 0xffff0000, v70
	v_lshlrev_b32_e32 v70, 16, v71
	v_and_b32_e32 v71, 0xffff0000, v71
	v_lshl_add_u64 v[68:69], s[12:13], 0, v[68:69]
	v_pk_fma_f32 v[60:61], v[60:61], 0.5, v[104:105] op_sel_hi:[1,0,1]
	v_pk_fma_f32 v[58:59], v[58:59], 0.5, v[70:71] op_sel_hi:[1,0,1]
	v_pk_fma_f32 v[56:57], v[56:57], 0.5, v[106:107] op_sel_hi:[1,0,1]
	v_lshl_add_u64 v[68:69], v[68:69], 0, v[144:145]
	global_store_dwordx4 v[68:69], v[60:63], off sc0 sc1
	global_store_dwordx4 v[68:69], v[56:59], off offset:16 sc0 sc1
	s_nop 0
	v_lshlrev_b32_e32 v60, 16, v74
	v_lshlrev_b32_e32 v56, 16, v72
	v_and_b32_e32 v57, 0xffff0000, v72
	v_lshlrev_b32_e32 v58, 16, v73
	v_and_b32_e32 v59, 0xffff0000, v73
	v_and_b32_e32 v61, 0xffff0000, v74
	v_lshlrev_b32_e32 v62, 16, v75
	v_and_b32_e32 v63, 0xffff0000, v75
	v_pk_fma_f32 v[54:55], v[54:55], 0.5, v[58:59] op_sel_hi:[1,0,1]
	v_pk_fma_f32 v[52:53], v[52:53], 0.5, v[56:57] op_sel_hi:[1,0,1]
	v_pk_fma_f32 v[44:45], v[44:45], 0.5, v[60:61] op_sel_hi:[1,0,1]
	v_pk_fma_f32 v[46:47], v[46:47], 0.5, v[62:63] op_sel_hi:[1,0,1]
	global_store_dwordx4 v[68:69], v[52:55], off offset:512 sc0 sc1
	global_store_dwordx4 v[68:69], v[44:47], off offset:528 sc0 sc1
	s_nop 0
	v_lshlrev_b32_e32 v52, 16, v78
	v_lshlrev_b32_e32 v44, 16, v76
	v_and_b32_e32 v45, 0xffff0000, v76
	v_pk_fma_f32 v[44:45], v[48:49], 0.5, v[44:45] op_sel_hi:[1,0,1]
	v_lshlrev_b64 v[48:49], 12, v[98:99]
	v_lshlrev_b32_e32 v46, 16, v77
	v_and_b32_e32 v47, 0xffff0000, v77
	v_and_b32_e32 v53, 0xffff0000, v78
	v_lshlrev_b32_e32 v54, 16, v79
	v_and_b32_e32 v55, 0xffff0000, v79
	v_lshl_add_u64 v[48:49], s[12:13], 0, v[48:49]
	v_pk_fma_f32 v[46:47], v[50:51], 0.5, v[46:47] op_sel_hi:[1,0,1]
	v_pk_fma_f32 v[42:43], v[42:43], 0.5, v[54:55] op_sel_hi:[1,0,1]
	v_pk_fma_f32 v[40:41], v[40:41], 0.5, v[52:53] op_sel_hi:[1,0,1]
	v_lshl_add_u64 v[48:49], v[48:49], 0, v[144:145]
	global_store_dwordx4 v[48:49], v[44:47], off sc0 sc1
	global_store_dwordx4 v[48:49], v[40:43], off offset:16 sc0 sc1
	s_nop 0
	v_lshlrev_b32_e32 v44, 16, v82
	v_lshlrev_b32_e32 v40, 16, v80
	v_and_b32_e32 v41, 0xffff0000, v80
	v_lshlrev_b32_e32 v42, 16, v81
	v_and_b32_e32 v43, 0xffff0000, v81
	v_and_b32_e32 v45, 0xffff0000, v82
	v_lshlrev_b32_e32 v46, 16, v83
	v_and_b32_e32 v47, 0xffff0000, v83
	v_pk_fma_f32 v[38:39], v[38:39], 0.5, v[42:43] op_sel_hi:[1,0,1]
	v_pk_fma_f32 v[36:37], v[36:37], 0.5, v[40:41] op_sel_hi:[1,0,1]
	v_pk_fma_f32 v[28:29], v[28:29], 0.5, v[44:45] op_sel_hi:[1,0,1]
	v_pk_fma_f32 v[30:31], v[30:31], 0.5, v[46:47] op_sel_hi:[1,0,1]
	global_store_dwordx4 v[48:49], v[36:39], off offset:512 sc0 sc1
	global_store_dwordx4 v[48:49], v[28:31], off offset:528 sc0 sc1
	s_nop 0
	v_lshlrev_b32_e32 v36, 16, v86
	v_lshlrev_b32_e32 v28, 16, v84
	v_and_b32_e32 v29, 0xffff0000, v84
	v_pk_fma_f32 v[28:29], v[32:33], 0.5, v[28:29] op_sel_hi:[1,0,1]
	v_lshlrev_b64 v[32:33], 12, v[100:101]
	v_lshlrev_b32_e32 v30, 16, v85
	v_and_b32_e32 v31, 0xffff0000, v85
	v_and_b32_e32 v37, 0xffff0000, v86
	v_lshlrev_b32_e32 v38, 16, v87
	v_and_b32_e32 v39, 0xffff0000, v87
	v_lshl_add_u64 v[32:33], s[12:13], 0, v[32:33]
	v_pk_fma_f32 v[30:31], v[34:35], 0.5, v[30:31] op_sel_hi:[1,0,1]
	v_pk_fma_f32 v[26:27], v[26:27], 0.5, v[38:39] op_sel_hi:[1,0,1]
	v_pk_fma_f32 v[24:25], v[24:25], 0.5, v[36:37] op_sel_hi:[1,0,1]
	v_lshl_add_u64 v[32:33], v[32:33], 0, v[144:145]
	global_store_dwordx4 v[32:33], v[28:31], off sc0 sc1
	global_store_dwordx4 v[32:33], v[24:27], off offset:16 sc0 sc1
	s_nop 0
	v_lshlrev_b32_e32 v28, 16, v90
	v_lshlrev_b32_e32 v24, 16, v88
	v_and_b32_e32 v25, 0xffff0000, v88
	v_lshlrev_b32_e32 v26, 16, v89
	v_and_b32_e32 v27, 0xffff0000, v89
	v_and_b32_e32 v29, 0xffff0000, v90
	v_lshlrev_b32_e32 v30, 16, v91
	v_and_b32_e32 v31, 0xffff0000, v91
	v_pk_fma_f32 v[22:23], v[22:23], 0.5, v[26:27] op_sel_hi:[1,0,1]
	v_pk_fma_f32 v[20:21], v[20:21], 0.5, v[24:25] op_sel_hi:[1,0,1]
	v_pk_fma_f32 v[12:13], v[12:13], 0.5, v[28:29] op_sel_hi:[1,0,1]
	v_pk_fma_f32 v[14:15], v[14:15], 0.5, v[30:31] op_sel_hi:[1,0,1]
	global_store_dwordx4 v[32:33], v[20:23], off offset:512 sc0 sc1
	global_store_dwordx4 v[32:33], v[12:15], off offset:528 sc0 sc1
	s_nop 0
	v_lshlrev_b32_e32 v20, 16, v94
	v_lshlrev_b32_e32 v12, 16, v92
	v_and_b32_e32 v13, 0xffff0000, v92
	v_pk_fma_f32 v[12:13], v[16:17], 0.5, v[12:13] op_sel_hi:[1,0,1]
	v_lshlrev_b64 v[16:17], 12, v[102:103]
	v_lshlrev_b32_e32 v14, 16, v93
	v_and_b32_e32 v15, 0xffff0000, v93
	v_and_b32_e32 v21, 0xffff0000, v94
	v_lshlrev_b32_e32 v22, 16, v95
	v_and_b32_e32 v23, 0xffff0000, v95
	v_lshl_add_u64 v[16:17], s[12:13], 0, v[16:17]
	v_pk_fma_f32 v[14:15], v[18:19], 0.5, v[14:15] op_sel_hi:[1,0,1]
	v_pk_fma_f32 v[10:11], v[10:11], 0.5, v[22:23] op_sel_hi:[1,0,1]
	v_pk_fma_f32 v[8:9], v[8:9], 0.5, v[20:21] op_sel_hi:[1,0,1]
	v_lshl_add_u64 v[16:17], v[16:17], 0, v[144:145]
	global_store_dwordx4 v[16:17], v[12:15], off sc0 sc1
	global_store_dwordx4 v[16:17], v[8:11], off offset:16 sc0 sc1
	s_nop 0
	v_lshlrev_b32_e32 v12, 16, v66
	v_lshlrev_b32_e32 v8, 16, v64
	v_and_b32_e32 v9, 0xffff0000, v64
	v_lshlrev_b32_e32 v10, 16, v65
	v_and_b32_e32 v11, 0xffff0000, v65
	v_and_b32_e32 v13, 0xffff0000, v66
	v_lshlrev_b32_e32 v14, 16, v67
	v_and_b32_e32 v15, 0xffff0000, v67
	v_pk_fma_f32 v[6:7], v[6:7], 0.5, v[10:11] op_sel_hi:[1,0,1]
	v_pk_fma_f32 v[4:5], v[4:5], 0.5, v[8:9] op_sel_hi:[1,0,1]
	v_pk_fma_f32 v[2:3], v[2:3], 0.5, v[14:15] op_sel_hi:[1,0,1]
	v_pk_fma_f32 v[0:1], v[0:1], 0.5, v[12:13] op_sel_hi:[1,0,1]
	global_store_dwordx4 v[16:17], v[4:7], off offset:512 sc0 sc1
	global_store_dwordx4 v[16:17], v[0:3], off offset:528 sc0 sc1
	s_cbranch_vccz .LBB0_696
	s_waitcnt vmcnt(0)
	s_cmpk_gt_u32 s20, 0xff
	s_cbranch_scc1 .LBB0_711
	s_barrier
